# wout main loop hand-scheduled as well
# speedup vs baseline: 1.2629x; 1.0047x over previous
; template <bool GATHER>
; DI void gemm256_main(const h16* __restrict__ A, int lda, const int* __restrict__ idx, int m0,
;                      const h16* __restrict__ B, int ldb, int n0, int K, h16* lds, f16v (&acc)[4][2]) {
;   const int tid = otid512(), lane = tid & 63, wv = tid >> 6, wm = wv >> 2, wn = wv & 3;
;   const int lr = tid >> 1, lc = (tid & 1) * 32;
;   unsigned ao = (unsigned)(GATHER ? idx[m0 + lr] : (m0 + lr)) * (unsigned)lda + lc;
;   unsigned bo = (unsigned)(n0 + lr) * (unsigned)ldb + lc;
;   const h16* ap = A; const h16* bp = B;
;     ...
;   u4v ra[4], rb[4];
;   const int nk = K >> 6;
;   __syncthreads();
; #pragma unroll
;   for (int i = 0; i < 4; ++i) { ra[i] = *(const u4v*)(AP_ + 8 * i); rb[i] = *(const u4v*)(BP_ + 8 * i); }
;   ao += 64; bo += 64;
; #pragma unroll
;   for (int i = 0; i < 4; ++i) { *(u4v*)&lds[lr * LDH + lc + 8 * i] = ra[i]; *(u4v*)&lds[(256 + lr) * LDH + lc + 8 * i] = rb[i]; }
; #pragma unroll
;   for (int i = 0; i < 4; ++i) { ra[i] = *(const u4v*)(AP_ + 8 * i); rb[i] = *(const u4v*)(BP_ + 8 * i); }
;   ao += 64; bo += 64;
;   __syncthreads();
;   for (int kt = 0; kt < nk; ++kt) {
;     const h16* As = lds + (kt & 1) * (512 * LDH);
;     const h16* Bs = As + 256 * LDH;
;     h16* Wn = lds + ((kt & 1) ^ 1) * (512 * LDH);
;     if (kt + 1 < nk) {
; #pragma unroll
;       for (int i = 0; i < 4; ++i) { *(u4v*)&Wn[lr * LDH + lc + 8 * i] = ra[i]; *(u4v*)&Wn[(256 + lr) * LDH + lc + 8 * i] = rb[i]; }
;     }
;     if (kt + 2 < nk) {
; #pragma unroll
;       for (int i = 0; i < 4; ++i) { ra[i] = *(const u4v*)(AP_ + 8 * i); rb[i] = *(const u4v*)(BP_ + 8 * i); }
;       ao += 64; bo += 64;
;     }
; #pragma unroll
;     for (int ks = 0; ks < 4; ++ks) {
;       h8v af[4], bf[2];
; #pragma unroll
;       for (int i = 0; i < 4; ++i) af[i] = *(const h8v*)&As[(wm * 128 + i * 32 + (lane & 31)) * LDH + ks * 16 + 8 * (lane >> 5)];
; #pragma unroll
;       for (int j = 0; j < 2; ++j) bf[j] = *(const h8v*)&Bs[(wn * 64 + j * 32 + (lane & 31)) * LDH + ks * 16 + 8 * (lane >> 5)];
; #pragma unroll
; DI void phase_resid_gemm(const Params& p, const h16* A, int lda, const h16* W, int K, const float* xres, int bid, int nb, h16* lds) {
;     ...
;   for (int u = bid; u < 64 * 4; u += nb) {
;     const int m0 = (u >> 2) * 256, n0 = (u & 3) * 256;
;     f16v acc[4][2]; acc256_zero(acc);
;     gemm256_main<false>(A, lda, nullptr, m0, W, K, n0, K, lds, acc);
.LBB0_1354:
	s_lshl_b32 s5, s4, 6
	v_mov_b32_e32 v1, v180
	s_and_b32 s6, s5, 0xffffff00
	s_lshl_b32 s5, s4, 8
	s_and_b32 s5, s5, 0x300
	v_ashrrev_i32_e32 v58, 1, v1
	v_lshlrev_b32_e32 v2, 5, v1
	v_and_b32_e32 v60, 32, v2
	v_add_u32_e32 v2, s6, v58
	v_lshl_or_b32 v54, v2, 10, v60
	v_add_u32_e32 v2, s5, v58
	v_readlane_b32 s16, v254, 46
	v_lshl_or_b32 v56, v2, 10, v60
	v_mov_b32_e32 v55, v0
	v_mov_b32_e32 v57, v0
	v_readlane_b32 s17, v254, 47
	v_lshl_add_u64 v[2:3], v[54:55], 1, s[30:31]
	v_and_b32_e32 v55, 31, v1
	v_lshl_add_u64 v[4:5], v[56:57], 1, s[16:17]
	v_lshrrev_b32_e32 v57, 2, v1
	v_mul_lo_u32 v62, v58, s33
	v_mov_b32_e32 v59, v0
	v_and_or_b32 v55, v58, s56, v55
	v_and_b32_e32 v174, 8, v57
	v_add_u32_e32 v57, 16, v62
	v_or_b32_e32 v58, 64, v54
	v_mov_b32_e32 v61, v0
	v_mul_lo_u32 v171, v55, s33
	v_lshl_add_u32 v176, v60, 1, v57
	v_or_b32_e32 v60, 64, v56
	v_or_b32_e32 v164, 0x80, v54
	v_lshl_add_u64 v[54:55], v[58:59], 1, s[30:31]
	s_barrier
	v_readlane_b32 s16, v252, 3
	v_readlane_b32 s18, v252, 5
	v_readlane_b32 s19, v252, 6
	v_readlane_b32 s22, v252, 9
	v_readlane_b32 s17, v252, 4
	v_readlane_b32 s20, v252, 7
	v_readlane_b32 s21, v252, 8
	v_readlane_b32 s23, v252, 10
	s_nop 1
	s_add_i32 s4, s4, s22
	s_cmpk_gt_i32 s4, 0xff
	v_mov_b32_e32 v162, v2
	v_mov_b32_e32 v163, v3
	v_mov_b32_e32 v178, v4
	v_mov_b32_e32 v179, v5
	v_lshrrev_b32_e32 v199, 1, v180
	v_and_b32_e32 v244, 1, v180
	v_mul_u32_u24_e32 v199, 0x90, v199
	v_lshl_add_u32 v165, v244, 6, v199
	v_add_u32_e32 v165, 16, v165
	v_add_u32_e32 v175, 0x12000, v165
	v_lshrrev_b32_e32 v199, 8, v180
	v_and_b32_e32 v245, 31, v180
	v_lshl_or_b32 v199, v199, 7, v245
	v_mul_u32_u24_e32 v199, 0x90, v199
	v_bfe_u32 v244, v180, 5, 1
	v_lshl_add_u32 v199, v244, 4, v199
	v_add_u32_e32 v177, 16, v199
	v_add_u32_e32 v192, 0x12000, v177
	v_bfe_u32 v199, v180, 6, 2
	v_lshl_or_b32 v199, v199, 6, v245
	v_mul_u32_u24_e32 v199, 0x90, v199
	v_lshl_add_u32 v199, v244, 4, v199
	v_add_u32_e32 v193, 0x9010, v199
	v_add_u32_e32 v194, 0x12000, v193
	global_load_dwordx4 v[130:133], v[162:163], off offset:0
	global_load_dwordx4 v[134:137], v[162:163], off offset:16
	global_load_dwordx4 v[138:141], v[162:163], off offset:32
	global_load_dwordx4 v[142:145], v[162:163], off offset:48
	global_load_dwordx4 v[146:149], v[178:179], off offset:0
	global_load_dwordx4 v[150:153], v[178:179], off offset:16
	global_load_dwordx4 v[154:157], v[178:179], off offset:32
	global_load_dwordx4 v[158:161], v[178:179], off offset:48
	s_waitcnt vmcnt(0)
	ds_write_b128 v165, v[130:133]
	ds_write_b128 v165, v[134:137] offset:16
	ds_write_b128 v165, v[138:141] offset:32
	ds_write_b128 v165, v[142:145] offset:48
	ds_write_b128 v165, v[146:149] offset:36864
	ds_write_b128 v165, v[150:153] offset:36880
	ds_write_b128 v165, v[154:157] offset:36896
	ds_write_b128 v165, v[158:161] offset:36912
	global_load_dwordx4 v[130:133], v[162:163], off offset:128
	global_load_dwordx4 v[134:137], v[162:163], off offset:144
	global_load_dwordx4 v[138:141], v[162:163], off offset:160
	global_load_dwordx4 v[142:145], v[162:163], off offset:176
	global_load_dwordx4 v[146:149], v[178:179], off offset:128
	global_load_dwordx4 v[150:153], v[178:179], off offset:144
	global_load_dwordx4 v[154:157], v[178:179], off offset:160
	global_load_dwordx4 v[158:161], v[178:179], off offset:176
	s_waitcnt lgkmcnt(0)
	s_barrier
	ds_read_b128 v[228:231], v193
	ds_read_b128 v[188:191], v177
	ds_read_b128 v[232:235], v193 offset:4608
	ds_read_b128 v[200:203], v177 offset:4608
	ds_read_b128 v[204:207], v177 offset:9216
	ds_read_b128 v[208:211], v177 offset:13824
	ds_read_b128 v[236:239], v193 offset:32
	ds_read_b128 v[212:215], v177 offset:32
	ds_read_b128 v[240:243], v193 offset:4640
	ds_read_b128 v[216:219], v177 offset:4640
	ds_read_b128 v[220:223], v177 offset:9248
	ds_read_b128 v[224:227], v177 offset:13856
	s_waitcnt vmcnt(4)
	ds_write_b128 v175, v[130:133]
	ds_write_b128 v175, v[134:137] offset:16
	ds_write_b128 v175, v[138:141] offset:32
	ds_write_b128 v175, v[142:145] offset:48
	global_load_dwordx4 v[130:133], v[162:163], off offset:256
	global_load_dwordx4 v[134:137], v[162:163], off offset:272
	global_load_dwordx4 v[138:141], v[162:163], off offset:288
	global_load_dwordx4 v[142:145], v[162:163], off offset:304
	s_waitcnt lgkmcnt(14)
	v_mfma_f32_32x32x16_f16 v[114:129], v[228:231], v[188:191], 0
	s_waitcnt lgkmcnt(13)
	v_mfma_f32_32x32x16_f16 v[98:113], v[232:235], v[188:191], 0
	s_waitcnt lgkmcnt(12)
	v_mfma_f32_32x32x16_f16 v[82:97], v[228:231], v[200:203], 0
	v_mfma_f32_32x32x16_f16 v[66:81], v[232:235], v[200:203], 0
	s_waitcnt lgkmcnt(11)
	v_mfma_f32_32x32x16_f16 v[50:65], v[228:231], v[204:207], 0
	v_mfma_f32_32x32x16_f16 v[34:49], v[232:235], v[204:207], 0
	s_waitcnt lgkmcnt(10)
	v_mfma_f32_32x32x16_f16 v[18:33], v[228:231], v[208:211], 0
	v_mfma_f32_32x32x16_f16 v[2:17], v[232:235], v[208:211], 0
	ds_read_b128 v[228:231], v193 offset:64
	ds_read_b128 v[188:191], v177 offset:64
	ds_read_b128 v[232:235], v193 offset:4672
	ds_read_b128 v[200:203], v177 offset:4672
	ds_read_b128 v[204:207], v177 offset:9280
	ds_read_b128 v[208:211], v177 offset:13888
	s_waitcnt vmcnt(4)
	ds_write_b128 v175, v[146:149] offset:36864
	ds_write_b128 v175, v[150:153] offset:36880
	ds_write_b128 v175, v[154:157] offset:36896
	ds_write_b128 v175, v[158:161] offset:36912
	global_load_dwordx4 v[146:149], v[178:179], off offset:256
	global_load_dwordx4 v[150:153], v[178:179], off offset:272
	global_load_dwordx4 v[154:157], v[178:179], off offset:288
	global_load_dwordx4 v[158:161], v[178:179], off offset:304
	s_waitcnt lgkmcnt(15)
	v_mfma_f32_32x32x16_f16 v[114:129], v[236:239], v[212:215], v[114:129]
	s_waitcnt lgkmcnt(15)
; DI f16v mfma32(h8v a, h8v b, f16v c) { return __builtin_amdgcn_mfma_f32_32x32x16_f16(a, b, c, 0, 0, 0); }
; template <bool GATHER>
; DI void gemm256_main(const h16* __restrict__ A, int lda, const int* __restrict__ idx, int m0,
;                      const h16* __restrict__ B, int ldb, int n0, int K, h16* lds, f16v (&acc)[4][2]) {
;     ...
;   for (int kt = 0; kt < nk; ++kt) {
;     const h16* As = lds + (kt & 1) * (512 * LDH);
;     const h16* Bs = As + 256 * LDH;
;     h16* Wn = lds + ((kt & 1) ^ 1) * (512 * LDH);
;     if (kt + 1 < nk) {
; #pragma unroll
;       for (int i = 0; i < 4; ++i) { *(u4v*)&Wn[lr * LDH + lc + 8 * i] = ra[i]; *(u4v*)&Wn[(256 + lr) * LDH + lc + 8 * i] = rb[i]; }
;     }
;     if (kt + 2 < nk) {
; #pragma unroll
;       for (int i = 0; i < 4; ++i) { ra[i] = *(const u4v*)(AP_ + 8 * i); rb[i] = *(const u4v*)(BP_ + 8 * i); }
;       ao += 64; bo += 64;
;     }
; #pragma unroll
;     for (int ks = 0; ks < 4; ++ks) {
;       h8v af[4], bf[2];
; #pragma unroll
;       for (int i = 0; i < 4; ++i) af[i] = *(const h8v*)&As[(wm * 128 + i * 32 + (lane & 31)) * LDH + ks * 16 + 8 * (lane >> 5)];
; #pragma unroll
;       for (int j = 0; j < 2; ++j) bf[j] = *(const h8v*)&Bs[(wn * 64 + j * 32 + (lane & 31)) * LDH + ks * 16 + 8 * (lane >> 5)];
; #pragma unroll
;       for (int i = 0; i < 4; ++i)
; #pragma unroll
;         for (int j = 0; j < 2; ++j) acc[i][j] = mfma32(bf[j], af[i], acc[i][j]);
;     }
;     __syncthreads();
;   }
	v_mfma_f32_32x32x16_f16 v[98:113], v[240:243], v[212:215], v[98:113]
	s_waitcnt lgkmcnt(15)
	v_mfma_f32_32x32x16_f16 v[82:97], v[236:239], v[216:219], v[82:97]
	v_mfma_f32_32x32x16_f16 v[66:81], v[240:243], v[216:219], v[66:81]
	s_waitcnt lgkmcnt(15)
	v_mfma_f32_32x32x16_f16 v[50:65], v[236:239], v[220:223], v[50:65]
	v_mfma_f32_32x32x16_f16 v[34:49], v[240:243], v[220:223], v[34:49]
	s_waitcnt lgkmcnt(14)
	v_mfma_f32_32x32x16_f16 v[18:33], v[236:239], v[224:227], v[18:33]
	v_mfma_f32_32x32x16_f16 v[2:17], v[240:243], v[224:227], v[2:17]
	ds_read_b128 v[236:239], v193 offset:96
	ds_read_b128 v[212:215], v177 offset:96
	ds_read_b128 v[240:243], v193 offset:4704
	ds_read_b128 v[216:219], v177 offset:4704
	ds_read_b128 v[220:223], v177 offset:9312
	ds_read_b128 v[224:227], v177 offset:13920
	s_waitcnt lgkmcnt(14)
	v_mfma_f32_32x32x16_f16 v[114:129], v[228:231], v[188:191], v[114:129]
	s_waitcnt lgkmcnt(13)
	v_mfma_f32_32x32x16_f16 v[98:113], v[232:235], v[188:191], v[98:113]
	s_waitcnt lgkmcnt(12)
	v_mfma_f32_32x32x16_f16 v[82:97], v[228:231], v[200:203], v[82:97]
	v_mfma_f32_32x32x16_f16 v[66:81], v[232:235], v[200:203], v[66:81]
	s_waitcnt lgkmcnt(11)
	v_mfma_f32_32x32x16_f16 v[50:65], v[228:231], v[204:207], v[50:65]
	v_mfma_f32_32x32x16_f16 v[34:49], v[232:235], v[204:207], v[34:49]
	s_waitcnt lgkmcnt(10)
	v_mfma_f32_32x32x16_f16 v[18:33], v[228:231], v[208:211], v[18:33]
	v_mfma_f32_32x32x16_f16 v[2:17], v[232:235], v[208:211], v[2:17]
	s_waitcnt lgkmcnt(0)
	s_barrier
	ds_read_b128 v[228:231], v194
	ds_read_b128 v[188:191], v192
	ds_read_b128 v[232:235], v194 offset:4608
	ds_read_b128 v[200:203], v192 offset:4608
	ds_read_b128 v[204:207], v192 offset:9216
	ds_read_b128 v[208:211], v192 offset:13824
	v_mfma_f32_32x32x16_f16 v[114:129], v[236:239], v[212:215], v[114:129]
	v_mfma_f32_32x32x16_f16 v[98:113], v[240:243], v[212:215], v[98:113]
	v_mfma_f32_32x32x16_f16 v[82:97], v[236:239], v[216:219], v[82:97]
	v_mfma_f32_32x32x16_f16 v[66:81], v[240:243], v[216:219], v[66:81]
	v_mfma_f32_32x32x16_f16 v[50:65], v[236:239], v[220:223], v[50:65]
	v_mfma_f32_32x32x16_f16 v[34:49], v[240:243], v[220:223], v[34:49]
	v_mfma_f32_32x32x16_f16 v[18:33], v[236:239], v[224:227], v[18:33]
	v_mfma_f32_32x32x16_f16 v[2:17], v[240:243], v[224:227], v[2:17]
	ds_read_b128 v[236:239], v194 offset:32
	ds_read_b128 v[212:215], v192 offset:32
	ds_read_b128 v[240:243], v194 offset:4640
	ds_read_b128 v[216:219], v192 offset:4640
	ds_read_b128 v[220:223], v192 offset:9248
	ds_read_b128 v[224:227], v192 offset:13856
	s_waitcnt vmcnt(4)
	ds_write_b128 v165, v[130:133]
	ds_write_b128 v165, v[134:137] offset:16
	ds_write_b128 v165, v[138:141] offset:32
	ds_write_b128 v165, v[142:145] offset:48
	global_load_dwordx4 v[130:133], v[162:163], off offset:384
	global_load_dwordx4 v[134:137], v[162:163], off offset:400
	global_load_dwordx4 v[138:141], v[162:163], off offset:416
	global_load_dwordx4 v[142:145], v[162:163], off offset:432
	s_waitcnt lgkmcnt(14)
	v_mfma_f32_32x32x16_f16 v[114:129], v[228:231], v[188:191], v[114:129]
	s_waitcnt lgkmcnt(13)
	v_mfma_f32_32x32x16_f16 v[98:113], v[232:235], v[188:191], v[98:113]
	s_waitcnt lgkmcnt(12)
	v_mfma_f32_32x32x16_f16 v[82:97], v[228:231], v[200:203], v[82:97]
	v_mfma_f32_32x32x16_f16 v[66:81], v[232:235], v[200:203], v[66:81]
	s_waitcnt lgkmcnt(11)
	v_mfma_f32_32x32x16_f16 v[50:65], v[228:231], v[204:207], v[50:65]
	v_mfma_f32_32x32x16_f16 v[34:49], v[232:235], v[204:207], v[34:49]
	s_waitcnt lgkmcnt(10)
	v_mfma_f32_32x32x16_f16 v[18:33], v[228:231], v[208:211], v[18:33]
	v_mfma_f32_32x32x16_f16 v[2:17], v[232:235], v[208:211], v[2:17]
	ds_read_b128 v[228:231], v194 offset:64
	ds_read_b128 v[188:191], v192 offset:64
	ds_read_b128 v[232:235], v194 offset:4672
	ds_read_b128 v[200:203], v192 offset:4672
	ds_read_b128 v[204:207], v192 offset:9280
	ds_read_b128 v[208:211], v192 offset:13888
	s_waitcnt vmcnt(4)
	ds_write_b128 v165, v[146:149] offset:36864
	ds_write_b128 v165, v[150:153] offset:36880
	ds_write_b128 v165, v[154:157] offset:36896
	ds_write_b128 v165, v[158:161] offset:36912
	global_load_dwordx4 v[146:149], v[178:179], off offset:384
	global_load_dwordx4 v[150:153], v[178:179], off offset:400
	global_load_dwordx4 v[154:157], v[178:179], off offset:416
	global_load_dwordx4 v[158:161], v[178:179], off offset:432
	s_waitcnt lgkmcnt(15)
	v_mfma_f32_32x32x16_f16 v[114:129], v[236:239], v[212:215], v[114:129]
	s_waitcnt lgkmcnt(15)
	v_mfma_f32_32x32x16_f16 v[98:113], v[240:243], v[212:215], v[98:113]
	s_waitcnt lgkmcnt(15)
	v_mfma_f32_32x32x16_f16 v[82:97], v[236:239], v[216:219], v[82:97]
	v_mfma_f32_32x32x16_f16 v[66:81], v[240:243], v[216:219], v[66:81]
	s_waitcnt lgkmcnt(15)
	v_mfma_f32_32x32x16_f16 v[50:65], v[236:239], v[220:223], v[50:65]
	v_mfma_f32_32x32x16_f16 v[34:49], v[240:243], v[220:223], v[34:49]
	s_waitcnt lgkmcnt(14)
	v_mfma_f32_32x32x16_f16 v[18:33], v[236:239], v[224:227], v[18:33]
	v_mfma_f32_32x32x16_f16 v[2:17], v[240:243], v[224:227], v[2:17]
	ds_read_b128 v[236:239], v194 offset:96
	ds_read_b128 v[212:215], v192 offset:96
	ds_read_b128 v[240:243], v194 offset:4704
	ds_read_b128 v[216:219], v192 offset:4704
	ds_read_b128 v[220:223], v192 offset:9312
	ds_read_b128 v[224:227], v192 offset:13920
	s_waitcnt lgkmcnt(14)
	v_mfma_f32_32x32x16_f16 v[114:129], v[228:231], v[188:191], v[114:129]
	s_waitcnt lgkmcnt(13)
	v_mfma_f32_32x32x16_f16 v[98:113], v[232:235], v[188:191], v[98:113]
	s_waitcnt lgkmcnt(12)
	v_mfma_f32_32x32x16_f16 v[82:97], v[228:231], v[200:203], v[82:97]
	v_mfma_f32_32x32x16_f16 v[66:81], v[232:235], v[200:203], v[66:81]
	s_waitcnt lgkmcnt(11)
	v_mfma_f32_32x32x16_f16 v[50:65], v[228:231], v[204:207], v[50:65]
	v_mfma_f32_32x32x16_f16 v[34:49], v[232:235], v[204:207], v[34:49]
	s_waitcnt lgkmcnt(10)
	v_mfma_f32_32x32x16_f16 v[18:33], v[228:231], v[208:211], v[18:33]
	v_mfma_f32_32x32x16_f16 v[2:17], v[232:235], v[208:211], v[2:17]
	s_waitcnt lgkmcnt(0)
	s_barrier
; DI f16v mfma32(h8v a, h8v b, f16v c) { return __builtin_amdgcn_mfma_f32_32x32x16_f16(a, b, c, 0, 0, 0); }
; template <bool GATHER>
; DI void gemm256_main(const h16* __restrict__ A, int lda, const int* __restrict__ idx, int m0,
;                      const h16* __restrict__ B, int ldb, int n0, int K, h16* lds, f16v (&acc)[4][2]) {
;     ...
;   for (int kt = 0; kt < nk; ++kt) {
;     const h16* As = lds + (kt & 1) * (512 * LDH);
;     const h16* Bs = As + 256 * LDH;
;     h16* Wn = lds + ((kt & 1) ^ 1) * (512 * LDH);
;     if (kt + 1 < nk) {
; #pragma unroll
;       for (int i = 0; i < 4; ++i) { *(u4v*)&Wn[lr * LDH + lc + 8 * i] = ra[i]; *(u4v*)&Wn[(256 + lr) * LDH + lc + 8 * i] = rb[i]; }
;     }
;     if (kt + 2 < nk) {
; #pragma unroll
;       for (int i = 0; i < 4; ++i) { ra[i] = *(const u4v*)(AP_ + 8 * i); rb[i] = *(const u4v*)(BP_ + 8 * i); }
;       ao += 64; bo += 64;
;     }
; #pragma unroll
;     for (int ks = 0; ks < 4; ++ks) {
;       h8v af[4], bf[2];
; #pragma unroll
;       for (int i = 0; i < 4; ++i) af[i] = *(const h8v*)&As[(wm * 128 + i * 32 + (lane & 31)) * LDH + ks * 16 + 8 * (lane >> 5)];
; #pragma unroll
;       for (int j = 0; j < 2; ++j) bf[j] = *(const h8v*)&Bs[(wn * 64 + j * 32 + (lane & 31)) * LDH + ks * 16 + 8 * (lane >> 5)];
; #pragma unroll
;       for (int i = 0; i < 4; ++i)
; #pragma unroll
;         for (int j = 0; j < 2; ++j) acc[i][j] = mfma32(bf[j], af[i], acc[i][j]);
;     }
;     __syncthreads();
;   }
	ds_read_b128 v[228:231], v193
	ds_read_b128 v[188:191], v177
	ds_read_b128 v[232:235], v193 offset:4608
	ds_read_b128 v[200:203], v177 offset:4608
	ds_read_b128 v[204:207], v177 offset:9216
	ds_read_b128 v[208:211], v177 offset:13824
	v_mfma_f32_32x32x16_f16 v[114:129], v[236:239], v[212:215], v[114:129]
	v_mfma_f32_32x32x16_f16 v[98:113], v[240:243], v[212:215], v[98:113]
	v_mfma_f32_32x32x16_f16 v[82:97], v[236:239], v[216:219], v[82:97]
	v_mfma_f32_32x32x16_f16 v[66:81], v[240:243], v[216:219], v[66:81]
	v_mfma_f32_32x32x16_f16 v[50:65], v[236:239], v[220:223], v[50:65]
	v_mfma_f32_32x32x16_f16 v[34:49], v[240:243], v[220:223], v[34:49]
	v_mfma_f32_32x32x16_f16 v[18:33], v[236:239], v[224:227], v[18:33]
	v_mfma_f32_32x32x16_f16 v[2:17], v[240:243], v[224:227], v[2:17]
	ds_read_b128 v[236:239], v193 offset:32
	ds_read_b128 v[212:215], v177 offset:32
	ds_read_b128 v[240:243], v193 offset:4640
	ds_read_b128 v[216:219], v177 offset:4640
	ds_read_b128 v[220:223], v177 offset:9248
	ds_read_b128 v[224:227], v177 offset:13856
	s_waitcnt vmcnt(4)
	ds_write_b128 v175, v[130:133]
	ds_write_b128 v175, v[134:137] offset:16
	ds_write_b128 v175, v[138:141] offset:32
	ds_write_b128 v175, v[142:145] offset:48
	global_load_dwordx4 v[130:133], v[162:163], off offset:512
	global_load_dwordx4 v[134:137], v[162:163], off offset:528
	global_load_dwordx4 v[138:141], v[162:163], off offset:544
	global_load_dwordx4 v[142:145], v[162:163], off offset:560
	s_waitcnt lgkmcnt(14)
	v_mfma_f32_32x32x16_f16 v[114:129], v[228:231], v[188:191], v[114:129]
	s_waitcnt lgkmcnt(13)
	v_mfma_f32_32x32x16_f16 v[98:113], v[232:235], v[188:191], v[98:113]
	s_waitcnt lgkmcnt(12)
	v_mfma_f32_32x32x16_f16 v[82:97], v[228:231], v[200:203], v[82:97]
	v_mfma_f32_32x32x16_f16 v[66:81], v[232:235], v[200:203], v[66:81]
	s_waitcnt lgkmcnt(11)
	v_mfma_f32_32x32x16_f16 v[50:65], v[228:231], v[204:207], v[50:65]
	v_mfma_f32_32x32x16_f16 v[34:49], v[232:235], v[204:207], v[34:49]
	s_waitcnt lgkmcnt(10)
	v_mfma_f32_32x32x16_f16 v[18:33], v[228:231], v[208:211], v[18:33]
	v_mfma_f32_32x32x16_f16 v[2:17], v[232:235], v[208:211], v[2:17]
	ds_read_b128 v[228:231], v193 offset:64
	ds_read_b128 v[188:191], v177 offset:64
	ds_read_b128 v[232:235], v193 offset:4672
	ds_read_b128 v[200:203], v177 offset:4672
	ds_read_b128 v[204:207], v177 offset:9280
	ds_read_b128 v[208:211], v177 offset:13888
	s_waitcnt vmcnt(4)
	ds_write_b128 v175, v[146:149] offset:36864
	ds_write_b128 v175, v[150:153] offset:36880
	ds_write_b128 v175, v[154:157] offset:36896
	ds_write_b128 v175, v[158:161] offset:36912
	global_load_dwordx4 v[146:149], v[178:179], off offset:512
	global_load_dwordx4 v[150:153], v[178:179], off offset:528
	global_load_dwordx4 v[154:157], v[178:179], off offset:544
	global_load_dwordx4 v[158:161], v[178:179], off offset:560
	s_waitcnt lgkmcnt(15)
	v_mfma_f32_32x32x16_f16 v[114:129], v[236:239], v[212:215], v[114:129]
	s_waitcnt lgkmcnt(15)
	v_mfma_f32_32x32x16_f16 v[98:113], v[240:243], v[212:215], v[98:113]
	s_waitcnt lgkmcnt(15)
	v_mfma_f32_32x32x16_f16 v[82:97], v[236:239], v[216:219], v[82:97]
	v_mfma_f32_32x32x16_f16 v[66:81], v[240:243], v[216:219], v[66:81]
	s_waitcnt lgkmcnt(15)
	v_mfma_f32_32x32x16_f16 v[50:65], v[236:239], v[220:223], v[50:65]
	v_mfma_f32_32x32x16_f16 v[34:49], v[240:243], v[220:223], v[34:49]
	s_waitcnt lgkmcnt(14)
	v_mfma_f32_32x32x16_f16 v[18:33], v[236:239], v[224:227], v[18:33]
	v_mfma_f32_32x32x16_f16 v[2:17], v[240:243], v[224:227], v[2:17]
	ds_read_b128 v[236:239], v193 offset:96
	ds_read_b128 v[212:215], v177 offset:96
	ds_read_b128 v[240:243], v193 offset:4704
	ds_read_b128 v[216:219], v177 offset:4704
	ds_read_b128 v[220:223], v177 offset:9312
	ds_read_b128 v[224:227], v177 offset:13920
	s_waitcnt lgkmcnt(14)
	v_mfma_f32_32x32x16_f16 v[114:129], v[228:231], v[188:191], v[114:129]
	s_waitcnt lgkmcnt(13)
	v_mfma_f32_32x32x16_f16 v[98:113], v[232:235], v[188:191], v[98:113]
	s_waitcnt lgkmcnt(12)
	v_mfma_f32_32x32x16_f16 v[82:97], v[228:231], v[200:203], v[82:97]
	v_mfma_f32_32x32x16_f16 v[66:81], v[232:235], v[200:203], v[66:81]
	s_waitcnt lgkmcnt(11)
	v_mfma_f32_32x32x16_f16 v[50:65], v[228:231], v[204:207], v[50:65]
	v_mfma_f32_32x32x16_f16 v[34:49], v[232:235], v[204:207], v[34:49]
	s_waitcnt lgkmcnt(10)
	v_mfma_f32_32x32x16_f16 v[18:33], v[228:231], v[208:211], v[18:33]
	v_mfma_f32_32x32x16_f16 v[2:17], v[232:235], v[208:211], v[2:17]
	s_waitcnt lgkmcnt(0)
	s_barrier
; DI f16v mfma32(h8v a, h8v b, f16v c) { return __builtin_amdgcn_mfma_f32_32x32x16_f16(a, b, c, 0, 0, 0); }
; template <bool GATHER>
; DI void gemm256_main(const h16* __restrict__ A, int lda, const int* __restrict__ idx, int m0,
;                      const h16* __restrict__ B, int ldb, int n0, int K, h16* lds, f16v (&acc)[4][2]) {
;     ...
;   for (int kt = 0; kt < nk; ++kt) {
;     const h16* As = lds + (kt & 1) * (512 * LDH);
;     const h16* Bs = As + 256 * LDH;
;     h16* Wn = lds + ((kt & 1) ^ 1) * (512 * LDH);
;     if (kt + 1 < nk) {
; #pragma unroll
;       for (int i = 0; i < 4; ++i) { *(u4v*)&Wn[lr * LDH + lc + 8 * i] = ra[i]; *(u4v*)&Wn[(256 + lr) * LDH + lc + 8 * i] = rb[i]; }
;     }
;     if (kt + 2 < nk) {
; #pragma unroll
;       for (int i = 0; i < 4; ++i) { ra[i] = *(const u4v*)(AP_ + 8 * i); rb[i] = *(const u4v*)(BP_ + 8 * i); }
;       ao += 64; bo += 64;
;     }
; #pragma unroll
;     for (int ks = 0; ks < 4; ++ks) {
;       h8v af[4], bf[2];
; #pragma unroll
;       for (int i = 0; i < 4; ++i) af[i] = *(const h8v*)&As[(wm * 128 + i * 32 + (lane & 31)) * LDH + ks * 16 + 8 * (lane >> 5)];
; #pragma unroll
;       for (int j = 0; j < 2; ++j) bf[j] = *(const h8v*)&Bs[(wn * 64 + j * 32 + (lane & 31)) * LDH + ks * 16 + 8 * (lane >> 5)];
; #pragma unroll
;       for (int i = 0; i < 4; ++i)
; #pragma unroll
;         for (int j = 0; j < 2; ++j) acc[i][j] = mfma32(bf[j], af[i], acc[i][j]);
;     }
;     __syncthreads();
;   }
	ds_read_b128 v[228:231], v194
	ds_read_b128 v[188:191], v192
	ds_read_b128 v[232:235], v194 offset:4608
	ds_read_b128 v[200:203], v192 offset:4608
	ds_read_b128 v[204:207], v192 offset:9216
	ds_read_b128 v[208:211], v192 offset:13824
	v_mfma_f32_32x32x16_f16 v[114:129], v[236:239], v[212:215], v[114:129]
	v_mfma_f32_32x32x16_f16 v[98:113], v[240:243], v[212:215], v[98:113]
	v_mfma_f32_32x32x16_f16 v[82:97], v[236:239], v[216:219], v[82:97]
	v_mfma_f32_32x32x16_f16 v[66:81], v[240:243], v[216:219], v[66:81]
	v_mfma_f32_32x32x16_f16 v[50:65], v[236:239], v[220:223], v[50:65]
	v_mfma_f32_32x32x16_f16 v[34:49], v[240:243], v[220:223], v[34:49]
	v_mfma_f32_32x32x16_f16 v[18:33], v[236:239], v[224:227], v[18:33]
	v_mfma_f32_32x32x16_f16 v[2:17], v[240:243], v[224:227], v[2:17]
	ds_read_b128 v[236:239], v194 offset:32
	ds_read_b128 v[212:215], v192 offset:32
	ds_read_b128 v[240:243], v194 offset:4640
	ds_read_b128 v[216:219], v192 offset:4640
	ds_read_b128 v[220:223], v192 offset:9248
	ds_read_b128 v[224:227], v192 offset:13856
	s_waitcnt vmcnt(4)
	ds_write_b128 v165, v[130:133]
	ds_write_b128 v165, v[134:137] offset:16
	ds_write_b128 v165, v[138:141] offset:32
	ds_write_b128 v165, v[142:145] offset:48
	global_load_dwordx4 v[130:133], v[162:163], off offset:640
	global_load_dwordx4 v[134:137], v[162:163], off offset:656
	global_load_dwordx4 v[138:141], v[162:163], off offset:672
	global_load_dwordx4 v[142:145], v[162:163], off offset:688
	s_waitcnt lgkmcnt(14)
	v_mfma_f32_32x32x16_f16 v[114:129], v[228:231], v[188:191], v[114:129]
	s_waitcnt lgkmcnt(13)
	v_mfma_f32_32x32x16_f16 v[98:113], v[232:235], v[188:191], v[98:113]
	s_waitcnt lgkmcnt(12)
	v_mfma_f32_32x32x16_f16 v[82:97], v[228:231], v[200:203], v[82:97]
	v_mfma_f32_32x32x16_f16 v[66:81], v[232:235], v[200:203], v[66:81]
	s_waitcnt lgkmcnt(11)
	v_mfma_f32_32x32x16_f16 v[50:65], v[228:231], v[204:207], v[50:65]
	v_mfma_f32_32x32x16_f16 v[34:49], v[232:235], v[204:207], v[34:49]
	s_waitcnt lgkmcnt(10)
	v_mfma_f32_32x32x16_f16 v[18:33], v[228:231], v[208:211], v[18:33]
	v_mfma_f32_32x32x16_f16 v[2:17], v[232:235], v[208:211], v[2:17]
	ds_read_b128 v[228:231], v194 offset:64
	ds_read_b128 v[188:191], v192 offset:64
	ds_read_b128 v[232:235], v194 offset:4672
	ds_read_b128 v[200:203], v192 offset:4672
	ds_read_b128 v[204:207], v192 offset:9280
	ds_read_b128 v[208:211], v192 offset:13888
	s_waitcnt vmcnt(4)
	ds_write_b128 v165, v[146:149] offset:36864
	ds_write_b128 v165, v[150:153] offset:36880
	ds_write_b128 v165, v[154:157] offset:36896
	ds_write_b128 v165, v[158:161] offset:36912
	global_load_dwordx4 v[146:149], v[178:179], off offset:640
	global_load_dwordx4 v[150:153], v[178:179], off offset:656
	global_load_dwordx4 v[154:157], v[178:179], off offset:672
	global_load_dwordx4 v[158:161], v[178:179], off offset:688
	s_waitcnt lgkmcnt(15)
	v_mfma_f32_32x32x16_f16 v[114:129], v[236:239], v[212:215], v[114:129]
	s_waitcnt lgkmcnt(15)
	v_mfma_f32_32x32x16_f16 v[98:113], v[240:243], v[212:215], v[98:113]
	s_waitcnt lgkmcnt(15)
	v_mfma_f32_32x32x16_f16 v[82:97], v[236:239], v[216:219], v[82:97]
	v_mfma_f32_32x32x16_f16 v[66:81], v[240:243], v[216:219], v[66:81]
	s_waitcnt lgkmcnt(15)
	v_mfma_f32_32x32x16_f16 v[50:65], v[236:239], v[220:223], v[50:65]
	v_mfma_f32_32x32x16_f16 v[34:49], v[240:243], v[220:223], v[34:49]
	s_waitcnt lgkmcnt(14)
	v_mfma_f32_32x32x16_f16 v[18:33], v[236:239], v[224:227], v[18:33]
	v_mfma_f32_32x32x16_f16 v[2:17], v[240:243], v[224:227], v[2:17]
	ds_read_b128 v[236:239], v194 offset:96
	ds_read_b128 v[212:215], v192 offset:96
	ds_read_b128 v[240:243], v194 offset:4704
	ds_read_b128 v[216:219], v192 offset:4704
	ds_read_b128 v[220:223], v192 offset:9312
	ds_read_b128 v[224:227], v192 offset:13920
	s_waitcnt lgkmcnt(14)
	v_mfma_f32_32x32x16_f16 v[114:129], v[228:231], v[188:191], v[114:129]
	s_waitcnt lgkmcnt(13)
	v_mfma_f32_32x32x16_f16 v[98:113], v[232:235], v[188:191], v[98:113]
	s_waitcnt lgkmcnt(12)
	v_mfma_f32_32x32x16_f16 v[82:97], v[228:231], v[200:203], v[82:97]
	v_mfma_f32_32x32x16_f16 v[66:81], v[232:235], v[200:203], v[66:81]
	s_waitcnt lgkmcnt(11)
	v_mfma_f32_32x32x16_f16 v[50:65], v[228:231], v[204:207], v[50:65]
	v_mfma_f32_32x32x16_f16 v[34:49], v[232:235], v[204:207], v[34:49]
	s_waitcnt lgkmcnt(10)
	v_mfma_f32_32x32x16_f16 v[18:33], v[228:231], v[208:211], v[18:33]
	v_mfma_f32_32x32x16_f16 v[2:17], v[232:235], v[208:211], v[2:17]
	s_waitcnt lgkmcnt(0)
	s_barrier
; DI f16v mfma32(h8v a, h8v b, f16v c) { return __builtin_amdgcn_mfma_f32_32x32x16_f16(a, b, c, 0, 0, 0); }
; template <bool GATHER>
; DI void gemm256_main(const h16* __restrict__ A, int lda, const int* __restrict__ idx, int m0,
;                      const h16* __restrict__ B, int ldb, int n0, int K, h16* lds, f16v (&acc)[4][2]) {
;     ...
;   for (int kt = 0; kt < nk; ++kt) {
;     const h16* As = lds + (kt & 1) * (512 * LDH);
;     const h16* Bs = As + 256 * LDH;
;     h16* Wn = lds + ((kt & 1) ^ 1) * (512 * LDH);
;     if (kt + 1 < nk) {
; #pragma unroll
;       for (int i = 0; i < 4; ++i) { *(u4v*)&Wn[lr * LDH + lc + 8 * i] = ra[i]; *(u4v*)&Wn[(256 + lr) * LDH + lc + 8 * i] = rb[i]; }
;     }
;     if (kt + 2 < nk) {
; #pragma unroll
;       for (int i = 0; i < 4; ++i) { ra[i] = *(const u4v*)(AP_ + 8 * i); rb[i] = *(const u4v*)(BP_ + 8 * i); }
;       ao += 64; bo += 64;
;     }
; #pragma unroll
;     for (int ks = 0; ks < 4; ++ks) {
;       h8v af[4], bf[2];
; #pragma unroll
;       for (int i = 0; i < 4; ++i) af[i] = *(const h8v*)&As[(wm * 128 + i * 32 + (lane & 31)) * LDH + ks * 16 + 8 * (lane >> 5)];
; #pragma unroll
;       for (int j = 0; j < 2; ++j) bf[j] = *(const h8v*)&Bs[(wn * 64 + j * 32 + (lane & 31)) * LDH + ks * 16 + 8 * (lane >> 5)];
; #pragma unroll
;       for (int i = 0; i < 4; ++i)
; #pragma unroll
;         for (int j = 0; j < 2; ++j) acc[i][j] = mfma32(bf[j], af[i], acc[i][j]);
;     }
;     __syncthreads();
;   }
	ds_read_b128 v[228:231], v193
	ds_read_b128 v[188:191], v177
	ds_read_b128 v[232:235], v193 offset:4608
	ds_read_b128 v[200:203], v177 offset:4608
	ds_read_b128 v[204:207], v177 offset:9216
	ds_read_b128 v[208:211], v177 offset:13824
	v_mfma_f32_32x32x16_f16 v[114:129], v[236:239], v[212:215], v[114:129]
	v_mfma_f32_32x32x16_f16 v[98:113], v[240:243], v[212:215], v[98:113]
	v_mfma_f32_32x32x16_f16 v[82:97], v[236:239], v[216:219], v[82:97]
	v_mfma_f32_32x32x16_f16 v[66:81], v[240:243], v[216:219], v[66:81]
	v_mfma_f32_32x32x16_f16 v[50:65], v[236:239], v[220:223], v[50:65]
	v_mfma_f32_32x32x16_f16 v[34:49], v[240:243], v[220:223], v[34:49]
	v_mfma_f32_32x32x16_f16 v[18:33], v[236:239], v[224:227], v[18:33]
	v_mfma_f32_32x32x16_f16 v[2:17], v[240:243], v[224:227], v[2:17]
	ds_read_b128 v[236:239], v193 offset:32
	ds_read_b128 v[212:215], v177 offset:32
	ds_read_b128 v[240:243], v193 offset:4640
	ds_read_b128 v[216:219], v177 offset:4640
	ds_read_b128 v[220:223], v177 offset:9248
	ds_read_b128 v[224:227], v177 offset:13856
	s_waitcnt vmcnt(4)
	ds_write_b128 v175, v[130:133]
	ds_write_b128 v175, v[134:137] offset:16
	ds_write_b128 v175, v[138:141] offset:32
	ds_write_b128 v175, v[142:145] offset:48
	global_load_dwordx4 v[130:133], v[162:163], off offset:768
	global_load_dwordx4 v[134:137], v[162:163], off offset:784
	global_load_dwordx4 v[138:141], v[162:163], off offset:800
	global_load_dwordx4 v[142:145], v[162:163], off offset:816
	s_waitcnt lgkmcnt(14)
	v_mfma_f32_32x32x16_f16 v[114:129], v[228:231], v[188:191], v[114:129]
	s_waitcnt lgkmcnt(13)
	v_mfma_f32_32x32x16_f16 v[98:113], v[232:235], v[188:191], v[98:113]
	s_waitcnt lgkmcnt(12)
	v_mfma_f32_32x32x16_f16 v[82:97], v[228:231], v[200:203], v[82:97]
	v_mfma_f32_32x32x16_f16 v[66:81], v[232:235], v[200:203], v[66:81]
	s_waitcnt lgkmcnt(11)
	v_mfma_f32_32x32x16_f16 v[50:65], v[228:231], v[204:207], v[50:65]
	v_mfma_f32_32x32x16_f16 v[34:49], v[232:235], v[204:207], v[34:49]
	s_waitcnt lgkmcnt(10)
	v_mfma_f32_32x32x16_f16 v[18:33], v[228:231], v[208:211], v[18:33]
	v_mfma_f32_32x32x16_f16 v[2:17], v[232:235], v[208:211], v[2:17]
	ds_read_b128 v[228:231], v193 offset:64
	ds_read_b128 v[188:191], v177 offset:64
	ds_read_b128 v[232:235], v193 offset:4672
	ds_read_b128 v[200:203], v177 offset:4672
	ds_read_b128 v[204:207], v177 offset:9280
	ds_read_b128 v[208:211], v177 offset:13888
	s_waitcnt vmcnt(4)
	ds_write_b128 v175, v[146:149] offset:36864
	ds_write_b128 v175, v[150:153] offset:36880
	ds_write_b128 v175, v[154:157] offset:36896
	ds_write_b128 v175, v[158:161] offset:36912
	global_load_dwordx4 v[146:149], v[178:179], off offset:768
	global_load_dwordx4 v[150:153], v[178:179], off offset:784
	global_load_dwordx4 v[154:157], v[178:179], off offset:800
	global_load_dwordx4 v[158:161], v[178:179], off offset:816
	s_waitcnt lgkmcnt(15)
	v_mfma_f32_32x32x16_f16 v[114:129], v[236:239], v[212:215], v[114:129]
	s_waitcnt lgkmcnt(15)
	v_mfma_f32_32x32x16_f16 v[98:113], v[240:243], v[212:215], v[98:113]
	s_waitcnt lgkmcnt(15)
	v_mfma_f32_32x32x16_f16 v[82:97], v[236:239], v[216:219], v[82:97]
	v_mfma_f32_32x32x16_f16 v[66:81], v[240:243], v[216:219], v[66:81]
	s_waitcnt lgkmcnt(15)
	v_mfma_f32_32x32x16_f16 v[50:65], v[236:239], v[220:223], v[50:65]
	v_mfma_f32_32x32x16_f16 v[34:49], v[240:243], v[220:223], v[34:49]
	s_waitcnt lgkmcnt(14)
	v_mfma_f32_32x32x16_f16 v[18:33], v[236:239], v[224:227], v[18:33]
	v_mfma_f32_32x32x16_f16 v[2:17], v[240:243], v[224:227], v[2:17]
	ds_read_b128 v[236:239], v193 offset:96
	ds_read_b128 v[212:215], v177 offset:96
	ds_read_b128 v[240:243], v193 offset:4704
	ds_read_b128 v[216:219], v177 offset:4704
	ds_read_b128 v[220:223], v177 offset:9312
	ds_read_b128 v[224:227], v177 offset:13920
	s_waitcnt lgkmcnt(14)
	v_mfma_f32_32x32x16_f16 v[114:129], v[228:231], v[188:191], v[114:129]
	s_waitcnt lgkmcnt(13)
	v_mfma_f32_32x32x16_f16 v[98:113], v[232:235], v[188:191], v[98:113]
	s_waitcnt lgkmcnt(12)
	v_mfma_f32_32x32x16_f16 v[82:97], v[228:231], v[200:203], v[82:97]
	v_mfma_f32_32x32x16_f16 v[66:81], v[232:235], v[200:203], v[66:81]
	s_waitcnt lgkmcnt(11)
	v_mfma_f32_32x32x16_f16 v[50:65], v[228:231], v[204:207], v[50:65]
	v_mfma_f32_32x32x16_f16 v[34:49], v[232:235], v[204:207], v[34:49]
	s_waitcnt lgkmcnt(10)
	v_mfma_f32_32x32x16_f16 v[18:33], v[228:231], v[208:211], v[18:33]
	v_mfma_f32_32x32x16_f16 v[2:17], v[232:235], v[208:211], v[2:17]
	s_waitcnt lgkmcnt(0)
	s_barrier
; DI f16v mfma32(h8v a, h8v b, f16v c) { return __builtin_amdgcn_mfma_f32_32x32x16_f16(a, b, c, 0, 0, 0); }
; template <bool GATHER>
; DI void gemm256_main(const h16* __restrict__ A, int lda, const int* __restrict__ idx, int m0,
;                      const h16* __restrict__ B, int ldb, int n0, int K, h16* lds, f16v (&acc)[4][2]) {
;     ...
;   for (int kt = 0; kt < nk; ++kt) {
;     const h16* As = lds + (kt & 1) * (512 * LDH);
;     const h16* Bs = As + 256 * LDH;
;     h16* Wn = lds + ((kt & 1) ^ 1) * (512 * LDH);
;     if (kt + 1 < nk) {
; #pragma unroll
;       for (int i = 0; i < 4; ++i) { *(u4v*)&Wn[lr * LDH + lc + 8 * i] = ra[i]; *(u4v*)&Wn[(256 + lr) * LDH + lc + 8 * i] = rb[i]; }
;     }
;     if (kt + 2 < nk) {
; #pragma unroll
;       for (int i = 0; i < 4; ++i) { ra[i] = *(const u4v*)(AP_ + 8 * i); rb[i] = *(const u4v*)(BP_ + 8 * i); }
;       ao += 64; bo += 64;
;     }
; #pragma unroll
;     for (int ks = 0; ks < 4; ++ks) {
;       h8v af[4], bf[2];
; #pragma unroll
;       for (int i = 0; i < 4; ++i) af[i] = *(const h8v*)&As[(wm * 128 + i * 32 + (lane & 31)) * LDH + ks * 16 + 8 * (lane >> 5)];
; #pragma unroll
;       for (int j = 0; j < 2; ++j) bf[j] = *(const h8v*)&Bs[(wn * 64 + j * 32 + (lane & 31)) * LDH + ks * 16 + 8 * (lane >> 5)];
; #pragma unroll
;       for (int i = 0; i < 4; ++i)
; #pragma unroll
;         for (int j = 0; j < 2; ++j) acc[i][j] = mfma32(bf[j], af[i], acc[i][j]);
;     }
;     __syncthreads();
;   }
	ds_read_b128 v[228:231], v194
	ds_read_b128 v[188:191], v192
	ds_read_b128 v[232:235], v194 offset:4608
	ds_read_b128 v[200:203], v192 offset:4608
	ds_read_b128 v[204:207], v192 offset:9216
	ds_read_b128 v[208:211], v192 offset:13824
	v_mfma_f32_32x32x16_f16 v[114:129], v[236:239], v[212:215], v[114:129]
	v_mfma_f32_32x32x16_f16 v[98:113], v[240:243], v[212:215], v[98:113]
	v_mfma_f32_32x32x16_f16 v[82:97], v[236:239], v[216:219], v[82:97]
	v_mfma_f32_32x32x16_f16 v[66:81], v[240:243], v[216:219], v[66:81]
	v_mfma_f32_32x32x16_f16 v[50:65], v[236:239], v[220:223], v[50:65]
	v_mfma_f32_32x32x16_f16 v[34:49], v[240:243], v[220:223], v[34:49]
	v_mfma_f32_32x32x16_f16 v[18:33], v[236:239], v[224:227], v[18:33]
	v_mfma_f32_32x32x16_f16 v[2:17], v[240:243], v[224:227], v[2:17]
	ds_read_b128 v[236:239], v194 offset:32
	ds_read_b128 v[212:215], v192 offset:32
	ds_read_b128 v[240:243], v194 offset:4640
	ds_read_b128 v[216:219], v192 offset:4640
	ds_read_b128 v[220:223], v192 offset:9248
	ds_read_b128 v[224:227], v192 offset:13856
	s_waitcnt vmcnt(4)
	ds_write_b128 v165, v[130:133]
	ds_write_b128 v165, v[134:137] offset:16
	ds_write_b128 v165, v[138:141] offset:32
	ds_write_b128 v165, v[142:145] offset:48
	global_load_dwordx4 v[130:133], v[162:163], off offset:896
	global_load_dwordx4 v[134:137], v[162:163], off offset:912
	global_load_dwordx4 v[138:141], v[162:163], off offset:928
	global_load_dwordx4 v[142:145], v[162:163], off offset:944
	s_waitcnt lgkmcnt(14)
	v_mfma_f32_32x32x16_f16 v[114:129], v[228:231], v[188:191], v[114:129]
	s_waitcnt lgkmcnt(13)
	v_mfma_f32_32x32x16_f16 v[98:113], v[232:235], v[188:191], v[98:113]
	s_waitcnt lgkmcnt(12)
	v_mfma_f32_32x32x16_f16 v[82:97], v[228:231], v[200:203], v[82:97]
	v_mfma_f32_32x32x16_f16 v[66:81], v[232:235], v[200:203], v[66:81]
	s_waitcnt lgkmcnt(11)
	v_mfma_f32_32x32x16_f16 v[50:65], v[228:231], v[204:207], v[50:65]
	v_mfma_f32_32x32x16_f16 v[34:49], v[232:235], v[204:207], v[34:49]
	s_waitcnt lgkmcnt(10)
	v_mfma_f32_32x32x16_f16 v[18:33], v[228:231], v[208:211], v[18:33]
	v_mfma_f32_32x32x16_f16 v[2:17], v[232:235], v[208:211], v[2:17]
	ds_read_b128 v[228:231], v194 offset:64
	ds_read_b128 v[188:191], v192 offset:64
	ds_read_b128 v[232:235], v194 offset:4672
	ds_read_b128 v[200:203], v192 offset:4672
	ds_read_b128 v[204:207], v192 offset:9280
	ds_read_b128 v[208:211], v192 offset:13888
	s_waitcnt vmcnt(4)
	ds_write_b128 v165, v[146:149] offset:36864
	ds_write_b128 v165, v[150:153] offset:36880
	ds_write_b128 v165, v[154:157] offset:36896
	ds_write_b128 v165, v[158:161] offset:36912
	global_load_dwordx4 v[146:149], v[178:179], off offset:896
	global_load_dwordx4 v[150:153], v[178:179], off offset:912
	global_load_dwordx4 v[154:157], v[178:179], off offset:928
	global_load_dwordx4 v[158:161], v[178:179], off offset:944
	s_waitcnt lgkmcnt(15)
	v_mfma_f32_32x32x16_f16 v[114:129], v[236:239], v[212:215], v[114:129]
	s_waitcnt lgkmcnt(15)
	v_mfma_f32_32x32x16_f16 v[98:113], v[240:243], v[212:215], v[98:113]
	s_waitcnt lgkmcnt(15)
	v_mfma_f32_32x32x16_f16 v[82:97], v[236:239], v[216:219], v[82:97]
	v_mfma_f32_32x32x16_f16 v[66:81], v[240:243], v[216:219], v[66:81]
	s_waitcnt lgkmcnt(15)
	v_mfma_f32_32x32x16_f16 v[50:65], v[236:239], v[220:223], v[50:65]
	v_mfma_f32_32x32x16_f16 v[34:49], v[240:243], v[220:223], v[34:49]
	s_waitcnt lgkmcnt(14)
	v_mfma_f32_32x32x16_f16 v[18:33], v[236:239], v[224:227], v[18:33]
	v_mfma_f32_32x32x16_f16 v[2:17], v[240:243], v[224:227], v[2:17]
	ds_read_b128 v[236:239], v194 offset:96
	ds_read_b128 v[212:215], v192 offset:96
	ds_read_b128 v[240:243], v194 offset:4704
	ds_read_b128 v[216:219], v192 offset:4704
	ds_read_b128 v[220:223], v192 offset:9312
	ds_read_b128 v[224:227], v192 offset:13920
	s_waitcnt lgkmcnt(14)
	v_mfma_f32_32x32x16_f16 v[114:129], v[228:231], v[188:191], v[114:129]
	s_waitcnt lgkmcnt(13)
	v_mfma_f32_32x32x16_f16 v[98:113], v[232:235], v[188:191], v[98:113]
	s_waitcnt lgkmcnt(12)
	v_mfma_f32_32x32x16_f16 v[82:97], v[228:231], v[200:203], v[82:97]
	v_mfma_f32_32x32x16_f16 v[66:81], v[232:235], v[200:203], v[66:81]
	s_waitcnt lgkmcnt(11)
	v_mfma_f32_32x32x16_f16 v[50:65], v[228:231], v[204:207], v[50:65]
	v_mfma_f32_32x32x16_f16 v[34:49], v[232:235], v[204:207], v[34:49]
	s_waitcnt lgkmcnt(10)
	v_mfma_f32_32x32x16_f16 v[18:33], v[228:231], v[208:211], v[18:33]
	v_mfma_f32_32x32x16_f16 v[2:17], v[232:235], v[208:211], v[2:17]
	s_waitcnt lgkmcnt(0)
	s_barrier
; DI f16v mfma32(h8v a, h8v b, f16v c) { return __builtin_amdgcn_mfma_f32_32x32x16_f16(a, b, c, 0, 0, 0); }
; template <bool GATHER>
; DI void gemm256_main(const h16* __restrict__ A, int lda, const int* __restrict__ idx, int m0,
;                      const h16* __restrict__ B, int ldb, int n0, int K, h16* lds, f16v (&acc)[4][2]) {
;     ...
;   for (int kt = 0; kt < nk; ++kt) {
;     const h16* As = lds + (kt & 1) * (512 * LDH);
;     const h16* Bs = As + 256 * LDH;
;     h16* Wn = lds + ((kt & 1) ^ 1) * (512 * LDH);
;     if (kt + 1 < nk) {
; #pragma unroll
;       for (int i = 0; i < 4; ++i) { *(u4v*)&Wn[lr * LDH + lc + 8 * i] = ra[i]; *(u4v*)&Wn[(256 + lr) * LDH + lc + 8 * i] = rb[i]; }
;     }
;     if (kt + 2 < nk) {
; #pragma unroll
;       for (int i = 0; i < 4; ++i) { ra[i] = *(const u4v*)(AP_ + 8 * i); rb[i] = *(const u4v*)(BP_ + 8 * i); }
;       ao += 64; bo += 64;
;     }
; #pragma unroll
;     for (int ks = 0; ks < 4; ++ks) {
;       h8v af[4], bf[2];
; #pragma unroll
;       for (int i = 0; i < 4; ++i) af[i] = *(const h8v*)&As[(wm * 128 + i * 32 + (lane & 31)) * LDH + ks * 16 + 8 * (lane >> 5)];
; #pragma unroll
;       for (int j = 0; j < 2; ++j) bf[j] = *(const h8v*)&Bs[(wn * 64 + j * 32 + (lane & 31)) * LDH + ks * 16 + 8 * (lane >> 5)];
; #pragma unroll
;       for (int i = 0; i < 4; ++i)
; #pragma unroll
;         for (int j = 0; j < 2; ++j) acc[i][j] = mfma32(bf[j], af[i], acc[i][j]);
;     }
;     __syncthreads();
;   }
	ds_read_b128 v[228:231], v193
	ds_read_b128 v[188:191], v177
	ds_read_b128 v[232:235], v193 offset:4608
	ds_read_b128 v[200:203], v177 offset:4608
	ds_read_b128 v[204:207], v177 offset:9216
	ds_read_b128 v[208:211], v177 offset:13824
	v_mfma_f32_32x32x16_f16 v[114:129], v[236:239], v[212:215], v[114:129]
	v_mfma_f32_32x32x16_f16 v[98:113], v[240:243], v[212:215], v[98:113]
	v_mfma_f32_32x32x16_f16 v[82:97], v[236:239], v[216:219], v[82:97]
	v_mfma_f32_32x32x16_f16 v[66:81], v[240:243], v[216:219], v[66:81]
	v_mfma_f32_32x32x16_f16 v[50:65], v[236:239], v[220:223], v[50:65]
	v_mfma_f32_32x32x16_f16 v[34:49], v[240:243], v[220:223], v[34:49]
	v_mfma_f32_32x32x16_f16 v[18:33], v[236:239], v[224:227], v[18:33]
	v_mfma_f32_32x32x16_f16 v[2:17], v[240:243], v[224:227], v[2:17]
	ds_read_b128 v[236:239], v193 offset:32
	ds_read_b128 v[212:215], v177 offset:32
	ds_read_b128 v[240:243], v193 offset:4640
	ds_read_b128 v[216:219], v177 offset:4640
	ds_read_b128 v[220:223], v177 offset:9248
	ds_read_b128 v[224:227], v177 offset:13856
	s_waitcnt vmcnt(4)
	ds_write_b128 v175, v[130:133]
	ds_write_b128 v175, v[134:137] offset:16
	ds_write_b128 v175, v[138:141] offset:32
	ds_write_b128 v175, v[142:145] offset:48
	global_load_dwordx4 v[130:133], v[162:163], off offset:1024
	global_load_dwordx4 v[134:137], v[162:163], off offset:1040
	global_load_dwordx4 v[138:141], v[162:163], off offset:1056
	global_load_dwordx4 v[142:145], v[162:163], off offset:1072
	s_waitcnt lgkmcnt(14)
	v_mfma_f32_32x32x16_f16 v[114:129], v[228:231], v[188:191], v[114:129]
	s_waitcnt lgkmcnt(13)
	v_mfma_f32_32x32x16_f16 v[98:113], v[232:235], v[188:191], v[98:113]
	s_waitcnt lgkmcnt(12)
	v_mfma_f32_32x32x16_f16 v[82:97], v[228:231], v[200:203], v[82:97]
	v_mfma_f32_32x32x16_f16 v[66:81], v[232:235], v[200:203], v[66:81]
	s_waitcnt lgkmcnt(11)
	v_mfma_f32_32x32x16_f16 v[50:65], v[228:231], v[204:207], v[50:65]
	v_mfma_f32_32x32x16_f16 v[34:49], v[232:235], v[204:207], v[34:49]
	s_waitcnt lgkmcnt(10)
	v_mfma_f32_32x32x16_f16 v[18:33], v[228:231], v[208:211], v[18:33]
	v_mfma_f32_32x32x16_f16 v[2:17], v[232:235], v[208:211], v[2:17]
	ds_read_b128 v[228:231], v193 offset:64
	ds_read_b128 v[188:191], v177 offset:64
	ds_read_b128 v[232:235], v193 offset:4672
	ds_read_b128 v[200:203], v177 offset:4672
	ds_read_b128 v[204:207], v177 offset:9280
	ds_read_b128 v[208:211], v177 offset:13888
	s_waitcnt vmcnt(4)
	ds_write_b128 v175, v[146:149] offset:36864
	ds_write_b128 v175, v[150:153] offset:36880
	ds_write_b128 v175, v[154:157] offset:36896
	ds_write_b128 v175, v[158:161] offset:36912
	global_load_dwordx4 v[146:149], v[178:179], off offset:1024
	global_load_dwordx4 v[150:153], v[178:179], off offset:1040
	global_load_dwordx4 v[154:157], v[178:179], off offset:1056
	global_load_dwordx4 v[158:161], v[178:179], off offset:1072
	s_waitcnt lgkmcnt(15)
	v_mfma_f32_32x32x16_f16 v[114:129], v[236:239], v[212:215], v[114:129]
	s_waitcnt lgkmcnt(15)
	v_mfma_f32_32x32x16_f16 v[98:113], v[240:243], v[212:215], v[98:113]
	s_waitcnt lgkmcnt(15)
	v_mfma_f32_32x32x16_f16 v[82:97], v[236:239], v[216:219], v[82:97]
	v_mfma_f32_32x32x16_f16 v[66:81], v[240:243], v[216:219], v[66:81]
	s_waitcnt lgkmcnt(15)
	v_mfma_f32_32x32x16_f16 v[50:65], v[236:239], v[220:223], v[50:65]
	v_mfma_f32_32x32x16_f16 v[34:49], v[240:243], v[220:223], v[34:49]
	s_waitcnt lgkmcnt(14)
	v_mfma_f32_32x32x16_f16 v[18:33], v[236:239], v[224:227], v[18:33]
	v_mfma_f32_32x32x16_f16 v[2:17], v[240:243], v[224:227], v[2:17]
	ds_read_b128 v[236:239], v193 offset:96
	ds_read_b128 v[212:215], v177 offset:96
	ds_read_b128 v[240:243], v193 offset:4704
	ds_read_b128 v[216:219], v177 offset:4704
	ds_read_b128 v[220:223], v177 offset:9312
	ds_read_b128 v[224:227], v177 offset:13920
	s_waitcnt lgkmcnt(14)
	v_mfma_f32_32x32x16_f16 v[114:129], v[228:231], v[188:191], v[114:129]
	s_waitcnt lgkmcnt(13)
	v_mfma_f32_32x32x16_f16 v[98:113], v[232:235], v[188:191], v[98:113]
	s_waitcnt lgkmcnt(12)
	v_mfma_f32_32x32x16_f16 v[82:97], v[228:231], v[200:203], v[82:97]
	v_mfma_f32_32x32x16_f16 v[66:81], v[232:235], v[200:203], v[66:81]
	s_waitcnt lgkmcnt(11)
	v_mfma_f32_32x32x16_f16 v[50:65], v[228:231], v[204:207], v[50:65]
	v_mfma_f32_32x32x16_f16 v[34:49], v[232:235], v[204:207], v[34:49]
	s_waitcnt lgkmcnt(10)
	v_mfma_f32_32x32x16_f16 v[18:33], v[228:231], v[208:211], v[18:33]
	v_mfma_f32_32x32x16_f16 v[2:17], v[232:235], v[208:211], v[2:17]
	s_waitcnt lgkmcnt(0)
	s_barrier
; DI f16v mfma32(h8v a, h8v b, f16v c) { return __builtin_amdgcn_mfma_f32_32x32x16_f16(a, b, c, 0, 0, 0); }
; template <bool GATHER>
; DI void gemm256_main(const h16* __restrict__ A, int lda, const int* __restrict__ idx, int m0,
;                      const h16* __restrict__ B, int ldb, int n0, int K, h16* lds, f16v (&acc)[4][2]) {
;     ...
;   for (int kt = 0; kt < nk; ++kt) {
;     const h16* As = lds + (kt & 1) * (512 * LDH);
;     const h16* Bs = As + 256 * LDH;
;     h16* Wn = lds + ((kt & 1) ^ 1) * (512 * LDH);
;     if (kt + 1 < nk) {
; #pragma unroll
;       for (int i = 0; i < 4; ++i) { *(u4v*)&Wn[lr * LDH + lc + 8 * i] = ra[i]; *(u4v*)&Wn[(256 + lr) * LDH + lc + 8 * i] = rb[i]; }
;     }
;     if (kt + 2 < nk) {
; #pragma unroll
;       for (int i = 0; i < 4; ++i) { ra[i] = *(const u4v*)(AP_ + 8 * i); rb[i] = *(const u4v*)(BP_ + 8 * i); }
;       ao += 64; bo += 64;
;     }
; #pragma unroll
;     for (int ks = 0; ks < 4; ++ks) {
;       h8v af[4], bf[2];
; #pragma unroll
;       for (int i = 0; i < 4; ++i) af[i] = *(const h8v*)&As[(wm * 128 + i * 32 + (lane & 31)) * LDH + ks * 16 + 8 * (lane >> 5)];
; #pragma unroll
;       for (int j = 0; j < 2; ++j) bf[j] = *(const h8v*)&Bs[(wn * 64 + j * 32 + (lane & 31)) * LDH + ks * 16 + 8 * (lane >> 5)];
; #pragma unroll
;       for (int i = 0; i < 4; ++i)
; #pragma unroll
;         for (int j = 0; j < 2; ++j) acc[i][j] = mfma32(bf[j], af[i], acc[i][j]);
;     }
;     __syncthreads();
;   }
	ds_read_b128 v[228:231], v194
	ds_read_b128 v[188:191], v192
	ds_read_b128 v[232:235], v194 offset:4608
	ds_read_b128 v[200:203], v192 offset:4608
	ds_read_b128 v[204:207], v192 offset:9216
	ds_read_b128 v[208:211], v192 offset:13824
	v_mfma_f32_32x32x16_f16 v[114:129], v[236:239], v[212:215], v[114:129]
	v_mfma_f32_32x32x16_f16 v[98:113], v[240:243], v[212:215], v[98:113]
	v_mfma_f32_32x32x16_f16 v[82:97], v[236:239], v[216:219], v[82:97]
	v_mfma_f32_32x32x16_f16 v[66:81], v[240:243], v[216:219], v[66:81]
	v_mfma_f32_32x32x16_f16 v[50:65], v[236:239], v[220:223], v[50:65]
	v_mfma_f32_32x32x16_f16 v[34:49], v[240:243], v[220:223], v[34:49]
	v_mfma_f32_32x32x16_f16 v[18:33], v[236:239], v[224:227], v[18:33]
	v_mfma_f32_32x32x16_f16 v[2:17], v[240:243], v[224:227], v[2:17]
	ds_read_b128 v[236:239], v194 offset:32
	ds_read_b128 v[212:215], v192 offset:32
	ds_read_b128 v[240:243], v194 offset:4640
	ds_read_b128 v[216:219], v192 offset:4640
	ds_read_b128 v[220:223], v192 offset:9248
	ds_read_b128 v[224:227], v192 offset:13856
	s_waitcnt vmcnt(4)
	ds_write_b128 v165, v[130:133]
	ds_write_b128 v165, v[134:137] offset:16
	ds_write_b128 v165, v[138:141] offset:32
	ds_write_b128 v165, v[142:145] offset:48
	global_load_dwordx4 v[130:133], v[162:163], off offset:1152
	global_load_dwordx4 v[134:137], v[162:163], off offset:1168
	global_load_dwordx4 v[138:141], v[162:163], off offset:1184
	global_load_dwordx4 v[142:145], v[162:163], off offset:1200
	s_waitcnt lgkmcnt(14)
	v_mfma_f32_32x32x16_f16 v[114:129], v[228:231], v[188:191], v[114:129]
	s_waitcnt lgkmcnt(13)
	v_mfma_f32_32x32x16_f16 v[98:113], v[232:235], v[188:191], v[98:113]
	s_waitcnt lgkmcnt(12)
	v_mfma_f32_32x32x16_f16 v[82:97], v[228:231], v[200:203], v[82:97]
	v_mfma_f32_32x32x16_f16 v[66:81], v[232:235], v[200:203], v[66:81]
	s_waitcnt lgkmcnt(11)
	v_mfma_f32_32x32x16_f16 v[50:65], v[228:231], v[204:207], v[50:65]
	v_mfma_f32_32x32x16_f16 v[34:49], v[232:235], v[204:207], v[34:49]
	s_waitcnt lgkmcnt(10)
	v_mfma_f32_32x32x16_f16 v[18:33], v[228:231], v[208:211], v[18:33]
	v_mfma_f32_32x32x16_f16 v[2:17], v[232:235], v[208:211], v[2:17]
	ds_read_b128 v[228:231], v194 offset:64
	ds_read_b128 v[188:191], v192 offset:64
	ds_read_b128 v[232:235], v194 offset:4672
	ds_read_b128 v[200:203], v192 offset:4672
	ds_read_b128 v[204:207], v192 offset:9280
	ds_read_b128 v[208:211], v192 offset:13888
	s_waitcnt vmcnt(4)
	ds_write_b128 v165, v[146:149] offset:36864
	ds_write_b128 v165, v[150:153] offset:36880
	ds_write_b128 v165, v[154:157] offset:36896
	ds_write_b128 v165, v[158:161] offset:36912
	global_load_dwordx4 v[146:149], v[178:179], off offset:1152
	global_load_dwordx4 v[150:153], v[178:179], off offset:1168
	global_load_dwordx4 v[154:157], v[178:179], off offset:1184
	global_load_dwordx4 v[158:161], v[178:179], off offset:1200
	s_waitcnt lgkmcnt(15)
	v_mfma_f32_32x32x16_f16 v[114:129], v[236:239], v[212:215], v[114:129]
	s_waitcnt lgkmcnt(15)
	v_mfma_f32_32x32x16_f16 v[98:113], v[240:243], v[212:215], v[98:113]
	s_waitcnt lgkmcnt(15)
	v_mfma_f32_32x32x16_f16 v[82:97], v[236:239], v[216:219], v[82:97]
	v_mfma_f32_32x32x16_f16 v[66:81], v[240:243], v[216:219], v[66:81]
	s_waitcnt lgkmcnt(15)
	v_mfma_f32_32x32x16_f16 v[50:65], v[236:239], v[220:223], v[50:65]
	v_mfma_f32_32x32x16_f16 v[34:49], v[240:243], v[220:223], v[34:49]
	s_waitcnt lgkmcnt(14)
	v_mfma_f32_32x32x16_f16 v[18:33], v[236:239], v[224:227], v[18:33]
	v_mfma_f32_32x32x16_f16 v[2:17], v[240:243], v[224:227], v[2:17]
	ds_read_b128 v[236:239], v194 offset:96
	ds_read_b128 v[212:215], v192 offset:96
	ds_read_b128 v[240:243], v194 offset:4704
	ds_read_b128 v[216:219], v192 offset:4704
	ds_read_b128 v[220:223], v192 offset:9312
	ds_read_b128 v[224:227], v192 offset:13920
	s_waitcnt lgkmcnt(14)
	v_mfma_f32_32x32x16_f16 v[114:129], v[228:231], v[188:191], v[114:129]
	s_waitcnt lgkmcnt(13)
	v_mfma_f32_32x32x16_f16 v[98:113], v[232:235], v[188:191], v[98:113]
	s_waitcnt lgkmcnt(12)
	v_mfma_f32_32x32x16_f16 v[82:97], v[228:231], v[200:203], v[82:97]
	v_mfma_f32_32x32x16_f16 v[66:81], v[232:235], v[200:203], v[66:81]
	s_waitcnt lgkmcnt(11)
	v_mfma_f32_32x32x16_f16 v[50:65], v[228:231], v[204:207], v[50:65]
	v_mfma_f32_32x32x16_f16 v[34:49], v[232:235], v[204:207], v[34:49]
	s_waitcnt lgkmcnt(10)
	v_mfma_f32_32x32x16_f16 v[18:33], v[228:231], v[208:211], v[18:33]
	v_mfma_f32_32x32x16_f16 v[2:17], v[232:235], v[208:211], v[2:17]
	s_waitcnt lgkmcnt(0)
	s_barrier
; DI f16v mfma32(h8v a, h8v b, f16v c) { return __builtin_amdgcn_mfma_f32_32x32x16_f16(a, b, c, 0, 0, 0); }
; template <bool GATHER>
; DI void gemm256_main(const h16* __restrict__ A, int lda, const int* __restrict__ idx, int m0,
;                      const h16* __restrict__ B, int ldb, int n0, int K, h16* lds, f16v (&acc)[4][2]) {
;     ...
;   for (int kt = 0; kt < nk; ++kt) {
;     const h16* As = lds + (kt & 1) * (512 * LDH);
;     const h16* Bs = As + 256 * LDH;
;     h16* Wn = lds + ((kt & 1) ^ 1) * (512 * LDH);
;     if (kt + 1 < nk) {
; #pragma unroll
;       for (int i = 0; i < 4; ++i) { *(u4v*)&Wn[lr * LDH + lc + 8 * i] = ra[i]; *(u4v*)&Wn[(256 + lr) * LDH + lc + 8 * i] = rb[i]; }
;     }
;     if (kt + 2 < nk) {
; #pragma unroll
;       for (int i = 0; i < 4; ++i) { ra[i] = *(const u4v*)(AP_ + 8 * i); rb[i] = *(const u4v*)(BP_ + 8 * i); }
;       ao += 64; bo += 64;
;     }
; #pragma unroll
;     for (int ks = 0; ks < 4; ++ks) {
;       h8v af[4], bf[2];
; #pragma unroll
;       for (int i = 0; i < 4; ++i) af[i] = *(const h8v*)&As[(wm * 128 + i * 32 + (lane & 31)) * LDH + ks * 16 + 8 * (lane >> 5)];
; #pragma unroll
;       for (int j = 0; j < 2; ++j) bf[j] = *(const h8v*)&Bs[(wn * 64 + j * 32 + (lane & 31)) * LDH + ks * 16 + 8 * (lane >> 5)];
; #pragma unroll
;       for (int i = 0; i < 4; ++i)
; #pragma unroll
;         for (int j = 0; j < 2; ++j) acc[i][j] = mfma32(bf[j], af[i], acc[i][j]);
;     }
;     __syncthreads();
;   }
	ds_read_b128 v[228:231], v193
	ds_read_b128 v[188:191], v177
	ds_read_b128 v[232:235], v193 offset:4608
	ds_read_b128 v[200:203], v177 offset:4608
	ds_read_b128 v[204:207], v177 offset:9216
	ds_read_b128 v[208:211], v177 offset:13824
	v_mfma_f32_32x32x16_f16 v[114:129], v[236:239], v[212:215], v[114:129]
	v_mfma_f32_32x32x16_f16 v[98:113], v[240:243], v[212:215], v[98:113]
	v_mfma_f32_32x32x16_f16 v[82:97], v[236:239], v[216:219], v[82:97]
	v_mfma_f32_32x32x16_f16 v[66:81], v[240:243], v[216:219], v[66:81]
	v_mfma_f32_32x32x16_f16 v[50:65], v[236:239], v[220:223], v[50:65]
	v_mfma_f32_32x32x16_f16 v[34:49], v[240:243], v[220:223], v[34:49]
	v_mfma_f32_32x32x16_f16 v[18:33], v[236:239], v[224:227], v[18:33]
	v_mfma_f32_32x32x16_f16 v[2:17], v[240:243], v[224:227], v[2:17]
	ds_read_b128 v[236:239], v193 offset:32
	ds_read_b128 v[212:215], v177 offset:32
	ds_read_b128 v[240:243], v193 offset:4640
	ds_read_b128 v[216:219], v177 offset:4640
	ds_read_b128 v[220:223], v177 offset:9248
	ds_read_b128 v[224:227], v177 offset:13856
	s_waitcnt vmcnt(4)
	ds_write_b128 v175, v[130:133]
	ds_write_b128 v175, v[134:137] offset:16
	ds_write_b128 v175, v[138:141] offset:32
	ds_write_b128 v175, v[142:145] offset:48
	global_load_dwordx4 v[130:133], v[162:163], off offset:1280
	global_load_dwordx4 v[134:137], v[162:163], off offset:1296
	global_load_dwordx4 v[138:141], v[162:163], off offset:1312
	global_load_dwordx4 v[142:145], v[162:163], off offset:1328
	s_waitcnt lgkmcnt(14)
	v_mfma_f32_32x32x16_f16 v[114:129], v[228:231], v[188:191], v[114:129]
	s_waitcnt lgkmcnt(13)
	v_mfma_f32_32x32x16_f16 v[98:113], v[232:235], v[188:191], v[98:113]
	s_waitcnt lgkmcnt(12)
	v_mfma_f32_32x32x16_f16 v[82:97], v[228:231], v[200:203], v[82:97]
	v_mfma_f32_32x32x16_f16 v[66:81], v[232:235], v[200:203], v[66:81]
	s_waitcnt lgkmcnt(11)
	v_mfma_f32_32x32x16_f16 v[50:65], v[228:231], v[204:207], v[50:65]
	v_mfma_f32_32x32x16_f16 v[34:49], v[232:235], v[204:207], v[34:49]
	s_waitcnt lgkmcnt(10)
	v_mfma_f32_32x32x16_f16 v[18:33], v[228:231], v[208:211], v[18:33]
	v_mfma_f32_32x32x16_f16 v[2:17], v[232:235], v[208:211], v[2:17]
	ds_read_b128 v[228:231], v193 offset:64
	ds_read_b128 v[188:191], v177 offset:64
	ds_read_b128 v[232:235], v193 offset:4672
	ds_read_b128 v[200:203], v177 offset:4672
	ds_read_b128 v[204:207], v177 offset:9280
	ds_read_b128 v[208:211], v177 offset:13888
	s_waitcnt vmcnt(4)
	ds_write_b128 v175, v[146:149] offset:36864
	ds_write_b128 v175, v[150:153] offset:36880
	ds_write_b128 v175, v[154:157] offset:36896
	ds_write_b128 v175, v[158:161] offset:36912
	global_load_dwordx4 v[146:149], v[178:179], off offset:1280
	global_load_dwordx4 v[150:153], v[178:179], off offset:1296
	global_load_dwordx4 v[154:157], v[178:179], off offset:1312
	global_load_dwordx4 v[158:161], v[178:179], off offset:1328
	s_waitcnt lgkmcnt(15)
	v_mfma_f32_32x32x16_f16 v[114:129], v[236:239], v[212:215], v[114:129]
	s_waitcnt lgkmcnt(15)
	v_mfma_f32_32x32x16_f16 v[98:113], v[240:243], v[212:215], v[98:113]
	s_waitcnt lgkmcnt(15)
	v_mfma_f32_32x32x16_f16 v[82:97], v[236:239], v[216:219], v[82:97]
	v_mfma_f32_32x32x16_f16 v[66:81], v[240:243], v[216:219], v[66:81]
	s_waitcnt lgkmcnt(15)
	v_mfma_f32_32x32x16_f16 v[50:65], v[236:239], v[220:223], v[50:65]
	v_mfma_f32_32x32x16_f16 v[34:49], v[240:243], v[220:223], v[34:49]
	s_waitcnt lgkmcnt(14)
	v_mfma_f32_32x32x16_f16 v[18:33], v[236:239], v[224:227], v[18:33]
	v_mfma_f32_32x32x16_f16 v[2:17], v[240:243], v[224:227], v[2:17]
	ds_read_b128 v[236:239], v193 offset:96
	ds_read_b128 v[212:215], v177 offset:96
	ds_read_b128 v[240:243], v193 offset:4704
	ds_read_b128 v[216:219], v177 offset:4704
	ds_read_b128 v[220:223], v177 offset:9312
	ds_read_b128 v[224:227], v177 offset:13920
	s_waitcnt lgkmcnt(14)
	v_mfma_f32_32x32x16_f16 v[114:129], v[228:231], v[188:191], v[114:129]
	s_waitcnt lgkmcnt(13)
	v_mfma_f32_32x32x16_f16 v[98:113], v[232:235], v[188:191], v[98:113]
	s_waitcnt lgkmcnt(12)
	v_mfma_f32_32x32x16_f16 v[82:97], v[228:231], v[200:203], v[82:97]
	v_mfma_f32_32x32x16_f16 v[66:81], v[232:235], v[200:203], v[66:81]
	s_waitcnt lgkmcnt(11)
	v_mfma_f32_32x32x16_f16 v[50:65], v[228:231], v[204:207], v[50:65]
	v_mfma_f32_32x32x16_f16 v[34:49], v[232:235], v[204:207], v[34:49]
	s_waitcnt lgkmcnt(10)
	v_mfma_f32_32x32x16_f16 v[18:33], v[228:231], v[208:211], v[18:33]
	v_mfma_f32_32x32x16_f16 v[2:17], v[232:235], v[208:211], v[2:17]
	s_waitcnt lgkmcnt(0)
	s_barrier
; DI f16v mfma32(h8v a, h8v b, f16v c) { return __builtin_amdgcn_mfma_f32_32x32x16_f16(a, b, c, 0, 0, 0); }
; template <bool GATHER>
; DI void gemm256_main(const h16* __restrict__ A, int lda, const int* __restrict__ idx, int m0,
;                      const h16* __restrict__ B, int ldb, int n0, int K, h16* lds, f16v (&acc)[4][2]) {
;     ...
;   for (int kt = 0; kt < nk; ++kt) {
;     const h16* As = lds + (kt & 1) * (512 * LDH);
;     const h16* Bs = As + 256 * LDH;
;     h16* Wn = lds + ((kt & 1) ^ 1) * (512 * LDH);
;     if (kt + 1 < nk) {
; #pragma unroll
;       for (int i = 0; i < 4; ++i) { *(u4v*)&Wn[lr * LDH + lc + 8 * i] = ra[i]; *(u4v*)&Wn[(256 + lr) * LDH + lc + 8 * i] = rb[i]; }
;     }
;     if (kt + 2 < nk) {
; #pragma unroll
;       for (int i = 0; i < 4; ++i) { ra[i] = *(const u4v*)(AP_ + 8 * i); rb[i] = *(const u4v*)(BP_ + 8 * i); }
;       ao += 64; bo += 64;
;     }
; #pragma unroll
;     for (int ks = 0; ks < 4; ++ks) {
;       h8v af[4], bf[2];
; #pragma unroll
;       for (int i = 0; i < 4; ++i) af[i] = *(const h8v*)&As[(wm * 128 + i * 32 + (lane & 31)) * LDH + ks * 16 + 8 * (lane >> 5)];
; #pragma unroll
;       for (int j = 0; j < 2; ++j) bf[j] = *(const h8v*)&Bs[(wn * 64 + j * 32 + (lane & 31)) * LDH + ks * 16 + 8 * (lane >> 5)];
; #pragma unroll
;       for (int i = 0; i < 4; ++i)
; #pragma unroll
;         for (int j = 0; j < 2; ++j) acc[i][j] = mfma32(bf[j], af[i], acc[i][j]);
;     }
;     __syncthreads();
;   }
	ds_read_b128 v[228:231], v194
	ds_read_b128 v[188:191], v192
	ds_read_b128 v[232:235], v194 offset:4608
	ds_read_b128 v[200:203], v192 offset:4608
	ds_read_b128 v[204:207], v192 offset:9216
	ds_read_b128 v[208:211], v192 offset:13824
	v_mfma_f32_32x32x16_f16 v[114:129], v[236:239], v[212:215], v[114:129]
	v_mfma_f32_32x32x16_f16 v[98:113], v[240:243], v[212:215], v[98:113]
	v_mfma_f32_32x32x16_f16 v[82:97], v[236:239], v[216:219], v[82:97]
	v_mfma_f32_32x32x16_f16 v[66:81], v[240:243], v[216:219], v[66:81]
	v_mfma_f32_32x32x16_f16 v[50:65], v[236:239], v[220:223], v[50:65]
	v_mfma_f32_32x32x16_f16 v[34:49], v[240:243], v[220:223], v[34:49]
	v_mfma_f32_32x32x16_f16 v[18:33], v[236:239], v[224:227], v[18:33]
	v_mfma_f32_32x32x16_f16 v[2:17], v[240:243], v[224:227], v[2:17]
	ds_read_b128 v[236:239], v194 offset:32
	ds_read_b128 v[212:215], v192 offset:32
	ds_read_b128 v[240:243], v194 offset:4640
	ds_read_b128 v[216:219], v192 offset:4640
	ds_read_b128 v[220:223], v192 offset:9248
	ds_read_b128 v[224:227], v192 offset:13856
	s_waitcnt vmcnt(4)
	ds_write_b128 v165, v[130:133]
	ds_write_b128 v165, v[134:137] offset:16
	ds_write_b128 v165, v[138:141] offset:32
	ds_write_b128 v165, v[142:145] offset:48
	global_load_dwordx4 v[130:133], v[162:163], off offset:1408
	global_load_dwordx4 v[134:137], v[162:163], off offset:1424
	global_load_dwordx4 v[138:141], v[162:163], off offset:1440
	global_load_dwordx4 v[142:145], v[162:163], off offset:1456
	s_waitcnt lgkmcnt(14)
	v_mfma_f32_32x32x16_f16 v[114:129], v[228:231], v[188:191], v[114:129]
	s_waitcnt lgkmcnt(13)
	v_mfma_f32_32x32x16_f16 v[98:113], v[232:235], v[188:191], v[98:113]
	s_waitcnt lgkmcnt(12)
	v_mfma_f32_32x32x16_f16 v[82:97], v[228:231], v[200:203], v[82:97]
	v_mfma_f32_32x32x16_f16 v[66:81], v[232:235], v[200:203], v[66:81]
	s_waitcnt lgkmcnt(11)
	v_mfma_f32_32x32x16_f16 v[50:65], v[228:231], v[204:207], v[50:65]
	v_mfma_f32_32x32x16_f16 v[34:49], v[232:235], v[204:207], v[34:49]
	s_waitcnt lgkmcnt(10)
	v_mfma_f32_32x32x16_f16 v[18:33], v[228:231], v[208:211], v[18:33]
	v_mfma_f32_32x32x16_f16 v[2:17], v[232:235], v[208:211], v[2:17]
	ds_read_b128 v[228:231], v194 offset:64
	ds_read_b128 v[188:191], v192 offset:64
	ds_read_b128 v[232:235], v194 offset:4672
	ds_read_b128 v[200:203], v192 offset:4672
	ds_read_b128 v[204:207], v192 offset:9280
	ds_read_b128 v[208:211], v192 offset:13888
	s_waitcnt vmcnt(4)
	ds_write_b128 v165, v[146:149] offset:36864
	ds_write_b128 v165, v[150:153] offset:36880
	ds_write_b128 v165, v[154:157] offset:36896
	ds_write_b128 v165, v[158:161] offset:36912
	global_load_dwordx4 v[146:149], v[178:179], off offset:1408
	global_load_dwordx4 v[150:153], v[178:179], off offset:1424
	global_load_dwordx4 v[154:157], v[178:179], off offset:1440
	global_load_dwordx4 v[158:161], v[178:179], off offset:1456
	s_waitcnt lgkmcnt(15)
	v_mfma_f32_32x32x16_f16 v[114:129], v[236:239], v[212:215], v[114:129]
	s_waitcnt lgkmcnt(15)
	v_mfma_f32_32x32x16_f16 v[98:113], v[240:243], v[212:215], v[98:113]
	s_waitcnt lgkmcnt(15)
	v_mfma_f32_32x32x16_f16 v[82:97], v[236:239], v[216:219], v[82:97]
	v_mfma_f32_32x32x16_f16 v[66:81], v[240:243], v[216:219], v[66:81]
	s_waitcnt lgkmcnt(15)
	v_mfma_f32_32x32x16_f16 v[50:65], v[236:239], v[220:223], v[50:65]
	v_mfma_f32_32x32x16_f16 v[34:49], v[240:243], v[220:223], v[34:49]
	s_waitcnt lgkmcnt(14)
	v_mfma_f32_32x32x16_f16 v[18:33], v[236:239], v[224:227], v[18:33]
	v_mfma_f32_32x32x16_f16 v[2:17], v[240:243], v[224:227], v[2:17]
	ds_read_b128 v[236:239], v194 offset:96
	ds_read_b128 v[212:215], v192 offset:96
	ds_read_b128 v[240:243], v194 offset:4704
	ds_read_b128 v[216:219], v192 offset:4704
	ds_read_b128 v[220:223], v192 offset:9312
	ds_read_b128 v[224:227], v192 offset:13920
	s_waitcnt lgkmcnt(14)
	v_mfma_f32_32x32x16_f16 v[114:129], v[228:231], v[188:191], v[114:129]
	s_waitcnt lgkmcnt(13)
	v_mfma_f32_32x32x16_f16 v[98:113], v[232:235], v[188:191], v[98:113]
	s_waitcnt lgkmcnt(12)
	v_mfma_f32_32x32x16_f16 v[82:97], v[228:231], v[200:203], v[82:97]
	v_mfma_f32_32x32x16_f16 v[66:81], v[232:235], v[200:203], v[66:81]
	s_waitcnt lgkmcnt(11)
	v_mfma_f32_32x32x16_f16 v[50:65], v[228:231], v[204:207], v[50:65]
	v_mfma_f32_32x32x16_f16 v[34:49], v[232:235], v[204:207], v[34:49]
	s_waitcnt lgkmcnt(10)
	v_mfma_f32_32x32x16_f16 v[18:33], v[228:231], v[208:211], v[18:33]
	v_mfma_f32_32x32x16_f16 v[2:17], v[232:235], v[208:211], v[2:17]
	s_waitcnt lgkmcnt(0)
	s_barrier
; DI f16v mfma32(h8v a, h8v b, f16v c) { return __builtin_amdgcn_mfma_f32_32x32x16_f16(a, b, c, 0, 0, 0); }
; template <bool GATHER>
; DI void gemm256_main(const h16* __restrict__ A, int lda, const int* __restrict__ idx, int m0,
;                      const h16* __restrict__ B, int ldb, int n0, int K, h16* lds, f16v (&acc)[4][2]) {
;     ...
;   for (int kt = 0; kt < nk; ++kt) {
;     const h16* As = lds + (kt & 1) * (512 * LDH);
;     const h16* Bs = As + 256 * LDH;
;     h16* Wn = lds + ((kt & 1) ^ 1) * (512 * LDH);
;     if (kt + 1 < nk) {
; #pragma unroll
;       for (int i = 0; i < 4; ++i) { *(u4v*)&Wn[lr * LDH + lc + 8 * i] = ra[i]; *(u4v*)&Wn[(256 + lr) * LDH + lc + 8 * i] = rb[i]; }
;     }
;     if (kt + 2 < nk) {
; #pragma unroll
;       for (int i = 0; i < 4; ++i) { ra[i] = *(const u4v*)(AP_ + 8 * i); rb[i] = *(const u4v*)(BP_ + 8 * i); }
;       ao += 64; bo += 64;
;     }
; #pragma unroll
;     for (int ks = 0; ks < 4; ++ks) {
;       h8v af[4], bf[2];
; #pragma unroll
;       for (int i = 0; i < 4; ++i) af[i] = *(const h8v*)&As[(wm * 128 + i * 32 + (lane & 31)) * LDH + ks * 16 + 8 * (lane >> 5)];
; #pragma unroll
;       for (int j = 0; j < 2; ++j) bf[j] = *(const h8v*)&Bs[(wn * 64 + j * 32 + (lane & 31)) * LDH + ks * 16 + 8 * (lane >> 5)];
; #pragma unroll
;       for (int i = 0; i < 4; ++i)
; #pragma unroll
;         for (int j = 0; j < 2; ++j) acc[i][j] = mfma32(bf[j], af[i], acc[i][j]);
;     }
;     __syncthreads();
;   }
	ds_read_b128 v[228:231], v193
	ds_read_b128 v[188:191], v177
	ds_read_b128 v[232:235], v193 offset:4608
	ds_read_b128 v[200:203], v177 offset:4608
	ds_read_b128 v[204:207], v177 offset:9216
	ds_read_b128 v[208:211], v177 offset:13824
	v_mfma_f32_32x32x16_f16 v[114:129], v[236:239], v[212:215], v[114:129]
	v_mfma_f32_32x32x16_f16 v[98:113], v[240:243], v[212:215], v[98:113]
	v_mfma_f32_32x32x16_f16 v[82:97], v[236:239], v[216:219], v[82:97]
	v_mfma_f32_32x32x16_f16 v[66:81], v[240:243], v[216:219], v[66:81]
	v_mfma_f32_32x32x16_f16 v[50:65], v[236:239], v[220:223], v[50:65]
	v_mfma_f32_32x32x16_f16 v[34:49], v[240:243], v[220:223], v[34:49]
	v_mfma_f32_32x32x16_f16 v[18:33], v[236:239], v[224:227], v[18:33]
	v_mfma_f32_32x32x16_f16 v[2:17], v[240:243], v[224:227], v[2:17]
	ds_read_b128 v[236:239], v193 offset:32
	ds_read_b128 v[212:215], v177 offset:32
	ds_read_b128 v[240:243], v193 offset:4640
	ds_read_b128 v[216:219], v177 offset:4640
	ds_read_b128 v[220:223], v177 offset:9248
	ds_read_b128 v[224:227], v177 offset:13856
	s_waitcnt vmcnt(4)
	ds_write_b128 v175, v[130:133]
	ds_write_b128 v175, v[134:137] offset:16
	ds_write_b128 v175, v[138:141] offset:32
	ds_write_b128 v175, v[142:145] offset:48
	global_load_dwordx4 v[130:133], v[162:163], off offset:1536
	global_load_dwordx4 v[134:137], v[162:163], off offset:1552
	global_load_dwordx4 v[138:141], v[162:163], off offset:1568
	global_load_dwordx4 v[142:145], v[162:163], off offset:1584
	s_waitcnt lgkmcnt(14)
	v_mfma_f32_32x32x16_f16 v[114:129], v[228:231], v[188:191], v[114:129]
	s_waitcnt lgkmcnt(13)
	v_mfma_f32_32x32x16_f16 v[98:113], v[232:235], v[188:191], v[98:113]
	s_waitcnt lgkmcnt(12)
	v_mfma_f32_32x32x16_f16 v[82:97], v[228:231], v[200:203], v[82:97]
	v_mfma_f32_32x32x16_f16 v[66:81], v[232:235], v[200:203], v[66:81]
	s_waitcnt lgkmcnt(11)
	v_mfma_f32_32x32x16_f16 v[50:65], v[228:231], v[204:207], v[50:65]
	v_mfma_f32_32x32x16_f16 v[34:49], v[232:235], v[204:207], v[34:49]
	s_waitcnt lgkmcnt(10)
	v_mfma_f32_32x32x16_f16 v[18:33], v[228:231], v[208:211], v[18:33]
	v_mfma_f32_32x32x16_f16 v[2:17], v[232:235], v[208:211], v[2:17]
	ds_read_b128 v[228:231], v193 offset:64
	ds_read_b128 v[188:191], v177 offset:64
	ds_read_b128 v[232:235], v193 offset:4672
	ds_read_b128 v[200:203], v177 offset:4672
	ds_read_b128 v[204:207], v177 offset:9280
	ds_read_b128 v[208:211], v177 offset:13888
	s_waitcnt vmcnt(4)
	ds_write_b128 v175, v[146:149] offset:36864
	ds_write_b128 v175, v[150:153] offset:36880
	ds_write_b128 v175, v[154:157] offset:36896
	ds_write_b128 v175, v[158:161] offset:36912
	global_load_dwordx4 v[146:149], v[178:179], off offset:1536
	global_load_dwordx4 v[150:153], v[178:179], off offset:1552
	global_load_dwordx4 v[154:157], v[178:179], off offset:1568
	global_load_dwordx4 v[158:161], v[178:179], off offset:1584
	s_waitcnt lgkmcnt(15)
	v_mfma_f32_32x32x16_f16 v[114:129], v[236:239], v[212:215], v[114:129]
	s_waitcnt lgkmcnt(15)
	v_mfma_f32_32x32x16_f16 v[98:113], v[240:243], v[212:215], v[98:113]
	s_waitcnt lgkmcnt(15)
	v_mfma_f32_32x32x16_f16 v[82:97], v[236:239], v[216:219], v[82:97]
	v_mfma_f32_32x32x16_f16 v[66:81], v[240:243], v[216:219], v[66:81]
	s_waitcnt lgkmcnt(15)
	v_mfma_f32_32x32x16_f16 v[50:65], v[236:239], v[220:223], v[50:65]
	v_mfma_f32_32x32x16_f16 v[34:49], v[240:243], v[220:223], v[34:49]
	s_waitcnt lgkmcnt(14)
	v_mfma_f32_32x32x16_f16 v[18:33], v[236:239], v[224:227], v[18:33]
	v_mfma_f32_32x32x16_f16 v[2:17], v[240:243], v[224:227], v[2:17]
	ds_read_b128 v[236:239], v193 offset:96
	ds_read_b128 v[212:215], v177 offset:96
	ds_read_b128 v[240:243], v193 offset:4704
	ds_read_b128 v[216:219], v177 offset:4704
	ds_read_b128 v[220:223], v177 offset:9312
	ds_read_b128 v[224:227], v177 offset:13920
	s_waitcnt lgkmcnt(14)
	v_mfma_f32_32x32x16_f16 v[114:129], v[228:231], v[188:191], v[114:129]
	s_waitcnt lgkmcnt(13)
	v_mfma_f32_32x32x16_f16 v[98:113], v[232:235], v[188:191], v[98:113]
	s_waitcnt lgkmcnt(12)
	v_mfma_f32_32x32x16_f16 v[82:97], v[228:231], v[200:203], v[82:97]
	v_mfma_f32_32x32x16_f16 v[66:81], v[232:235], v[200:203], v[66:81]
	s_waitcnt lgkmcnt(11)
	v_mfma_f32_32x32x16_f16 v[50:65], v[228:231], v[204:207], v[50:65]
	v_mfma_f32_32x32x16_f16 v[34:49], v[232:235], v[204:207], v[34:49]
	s_waitcnt lgkmcnt(10)
	v_mfma_f32_32x32x16_f16 v[18:33], v[228:231], v[208:211], v[18:33]
	v_mfma_f32_32x32x16_f16 v[2:17], v[232:235], v[208:211], v[2:17]
	s_waitcnt lgkmcnt(0)
	s_barrier
; DI f16v mfma32(h8v a, h8v b, f16v c) { return __builtin_amdgcn_mfma_f32_32x32x16_f16(a, b, c, 0, 0, 0); }
; template <bool GATHER>
; DI void gemm256_main(const h16* __restrict__ A, int lda, const int* __restrict__ idx, int m0,
;                      const h16* __restrict__ B, int ldb, int n0, int K, h16* lds, f16v (&acc)[4][2]) {
;     ...
;   for (int kt = 0; kt < nk; ++kt) {
;     const h16* As = lds + (kt & 1) * (512 * LDH);
;     const h16* Bs = As + 256 * LDH;
;     h16* Wn = lds + ((kt & 1) ^ 1) * (512 * LDH);
;     if (kt + 1 < nk) {
; #pragma unroll
;       for (int i = 0; i < 4; ++i) { *(u4v*)&Wn[lr * LDH + lc + 8 * i] = ra[i]; *(u4v*)&Wn[(256 + lr) * LDH + lc + 8 * i] = rb[i]; }
;     }
;     if (kt + 2 < nk) {
; #pragma unroll
;       for (int i = 0; i < 4; ++i) { ra[i] = *(const u4v*)(AP_ + 8 * i); rb[i] = *(const u4v*)(BP_ + 8 * i); }
;       ao += 64; bo += 64;
;     }
; #pragma unroll
;     for (int ks = 0; ks < 4; ++ks) {
;       h8v af[4], bf[2];
; #pragma unroll
;       for (int i = 0; i < 4; ++i) af[i] = *(const h8v*)&As[(wm * 128 + i * 32 + (lane & 31)) * LDH + ks * 16 + 8 * (lane >> 5)];
; #pragma unroll
;       for (int j = 0; j < 2; ++j) bf[j] = *(const h8v*)&Bs[(wn * 64 + j * 32 + (lane & 31)) * LDH + ks * 16 + 8 * (lane >> 5)];
; #pragma unroll
;       for (int i = 0; i < 4; ++i)
; #pragma unroll
;         for (int j = 0; j < 2; ++j) acc[i][j] = mfma32(bf[j], af[i], acc[i][j]);
;     }
;     __syncthreads();
;   }
	ds_read_b128 v[228:231], v194
	ds_read_b128 v[188:191], v192
	ds_read_b128 v[232:235], v194 offset:4608
	ds_read_b128 v[200:203], v192 offset:4608
	ds_read_b128 v[204:207], v192 offset:9216
	ds_read_b128 v[208:211], v192 offset:13824
	v_mfma_f32_32x32x16_f16 v[114:129], v[236:239], v[212:215], v[114:129]
	v_mfma_f32_32x32x16_f16 v[98:113], v[240:243], v[212:215], v[98:113]
	v_mfma_f32_32x32x16_f16 v[82:97], v[236:239], v[216:219], v[82:97]
	v_mfma_f32_32x32x16_f16 v[66:81], v[240:243], v[216:219], v[66:81]
	v_mfma_f32_32x32x16_f16 v[50:65], v[236:239], v[220:223], v[50:65]
	v_mfma_f32_32x32x16_f16 v[34:49], v[240:243], v[220:223], v[34:49]
	v_mfma_f32_32x32x16_f16 v[18:33], v[236:239], v[224:227], v[18:33]
	v_mfma_f32_32x32x16_f16 v[2:17], v[240:243], v[224:227], v[2:17]
	ds_read_b128 v[236:239], v194 offset:32
	ds_read_b128 v[212:215], v192 offset:32
	ds_read_b128 v[240:243], v194 offset:4640
	ds_read_b128 v[216:219], v192 offset:4640
	ds_read_b128 v[220:223], v192 offset:9248
	ds_read_b128 v[224:227], v192 offset:13856
	s_waitcnt vmcnt(4)
	ds_write_b128 v165, v[130:133]
	ds_write_b128 v165, v[134:137] offset:16
	ds_write_b128 v165, v[138:141] offset:32
	ds_write_b128 v165, v[142:145] offset:48
	global_load_dwordx4 v[130:133], v[162:163], off offset:1664
	global_load_dwordx4 v[134:137], v[162:163], off offset:1680
	global_load_dwordx4 v[138:141], v[162:163], off offset:1696
	global_load_dwordx4 v[142:145], v[162:163], off offset:1712
	s_waitcnt lgkmcnt(14)
	v_mfma_f32_32x32x16_f16 v[114:129], v[228:231], v[188:191], v[114:129]
	s_waitcnt lgkmcnt(13)
	v_mfma_f32_32x32x16_f16 v[98:113], v[232:235], v[188:191], v[98:113]
	s_waitcnt lgkmcnt(12)
	v_mfma_f32_32x32x16_f16 v[82:97], v[228:231], v[200:203], v[82:97]
	v_mfma_f32_32x32x16_f16 v[66:81], v[232:235], v[200:203], v[66:81]
	s_waitcnt lgkmcnt(11)
	v_mfma_f32_32x32x16_f16 v[50:65], v[228:231], v[204:207], v[50:65]
	v_mfma_f32_32x32x16_f16 v[34:49], v[232:235], v[204:207], v[34:49]
	s_waitcnt lgkmcnt(10)
	v_mfma_f32_32x32x16_f16 v[18:33], v[228:231], v[208:211], v[18:33]
	v_mfma_f32_32x32x16_f16 v[2:17], v[232:235], v[208:211], v[2:17]
	ds_read_b128 v[228:231], v194 offset:64
	ds_read_b128 v[188:191], v192 offset:64
	ds_read_b128 v[232:235], v194 offset:4672
	ds_read_b128 v[200:203], v192 offset:4672
	ds_read_b128 v[204:207], v192 offset:9280
	ds_read_b128 v[208:211], v192 offset:13888
	s_waitcnt vmcnt(4)
	ds_write_b128 v165, v[146:149] offset:36864
	ds_write_b128 v165, v[150:153] offset:36880
	ds_write_b128 v165, v[154:157] offset:36896
	ds_write_b128 v165, v[158:161] offset:36912
	global_load_dwordx4 v[146:149], v[178:179], off offset:1664
	global_load_dwordx4 v[150:153], v[178:179], off offset:1680
	global_load_dwordx4 v[154:157], v[178:179], off offset:1696
	global_load_dwordx4 v[158:161], v[178:179], off offset:1712
	s_waitcnt lgkmcnt(15)
	v_mfma_f32_32x32x16_f16 v[114:129], v[236:239], v[212:215], v[114:129]
	s_waitcnt lgkmcnt(15)
	v_mfma_f32_32x32x16_f16 v[98:113], v[240:243], v[212:215], v[98:113]
	s_waitcnt lgkmcnt(15)
	v_mfma_f32_32x32x16_f16 v[82:97], v[236:239], v[216:219], v[82:97]
	v_mfma_f32_32x32x16_f16 v[66:81], v[240:243], v[216:219], v[66:81]
	s_waitcnt lgkmcnt(15)
	v_mfma_f32_32x32x16_f16 v[50:65], v[236:239], v[220:223], v[50:65]
	v_mfma_f32_32x32x16_f16 v[34:49], v[240:243], v[220:223], v[34:49]
	s_waitcnt lgkmcnt(14)
	v_mfma_f32_32x32x16_f16 v[18:33], v[236:239], v[224:227], v[18:33]
	v_mfma_f32_32x32x16_f16 v[2:17], v[240:243], v[224:227], v[2:17]
	ds_read_b128 v[236:239], v194 offset:96
	ds_read_b128 v[212:215], v192 offset:96
	ds_read_b128 v[240:243], v194 offset:4704
	ds_read_b128 v[216:219], v192 offset:4704
	ds_read_b128 v[220:223], v192 offset:9312
	ds_read_b128 v[224:227], v192 offset:13920
	s_waitcnt lgkmcnt(14)
	v_mfma_f32_32x32x16_f16 v[114:129], v[228:231], v[188:191], v[114:129]
	s_waitcnt lgkmcnt(13)
	v_mfma_f32_32x32x16_f16 v[98:113], v[232:235], v[188:191], v[98:113]
	s_waitcnt lgkmcnt(12)
	v_mfma_f32_32x32x16_f16 v[82:97], v[228:231], v[200:203], v[82:97]
	v_mfma_f32_32x32x16_f16 v[66:81], v[232:235], v[200:203], v[66:81]
	s_waitcnt lgkmcnt(11)
	v_mfma_f32_32x32x16_f16 v[50:65], v[228:231], v[204:207], v[50:65]
	v_mfma_f32_32x32x16_f16 v[34:49], v[232:235], v[204:207], v[34:49]
	s_waitcnt lgkmcnt(10)
	v_mfma_f32_32x32x16_f16 v[18:33], v[228:231], v[208:211], v[18:33]
	v_mfma_f32_32x32x16_f16 v[2:17], v[232:235], v[208:211], v[2:17]
	s_waitcnt lgkmcnt(0)
	s_barrier
; DI f16v mfma32(h8v a, h8v b, f16v c) { return __builtin_amdgcn_mfma_f32_32x32x16_f16(a, b, c, 0, 0, 0); }
; template <bool GATHER>
; DI void gemm256_main(const h16* __restrict__ A, int lda, const int* __restrict__ idx, int m0,
;                      const h16* __restrict__ B, int ldb, int n0, int K, h16* lds, f16v (&acc)[4][2]) {
;     ...
;   for (int kt = 0; kt < nk; ++kt) {
;     const h16* As = lds + (kt & 1) * (512 * LDH);
;     const h16* Bs = As + 256 * LDH;
;     h16* Wn = lds + ((kt & 1) ^ 1) * (512 * LDH);
;     if (kt + 1 < nk) {
; #pragma unroll
;       for (int i = 0; i < 4; ++i) { *(u4v*)&Wn[lr * LDH + lc + 8 * i] = ra[i]; *(u4v*)&Wn[(256 + lr) * LDH + lc + 8 * i] = rb[i]; }
;     }
;     if (kt + 2 < nk) {
; #pragma unroll
;       for (int i = 0; i < 4; ++i) { ra[i] = *(const u4v*)(AP_ + 8 * i); rb[i] = *(const u4v*)(BP_ + 8 * i); }
;       ao += 64; bo += 64;
;     }
; #pragma unroll
;     for (int ks = 0; ks < 4; ++ks) {
;       h8v af[4], bf[2];
; #pragma unroll
;       for (int i = 0; i < 4; ++i) af[i] = *(const h8v*)&As[(wm * 128 + i * 32 + (lane & 31)) * LDH + ks * 16 + 8 * (lane >> 5)];
; #pragma unroll
;       for (int j = 0; j < 2; ++j) bf[j] = *(const h8v*)&Bs[(wn * 64 + j * 32 + (lane & 31)) * LDH + ks * 16 + 8 * (lane >> 5)];
; #pragma unroll
;       for (int i = 0; i < 4; ++i)
; #pragma unroll
;         for (int j = 0; j < 2; ++j) acc[i][j] = mfma32(bf[j], af[i], acc[i][j]);
;     }
;     __syncthreads();
;   }
	ds_read_b128 v[228:231], v193
	ds_read_b128 v[188:191], v177
	ds_read_b128 v[232:235], v193 offset:4608
	ds_read_b128 v[200:203], v177 offset:4608
	ds_read_b128 v[204:207], v177 offset:9216
	ds_read_b128 v[208:211], v177 offset:13824
	v_mfma_f32_32x32x16_f16 v[114:129], v[236:239], v[212:215], v[114:129]
	v_mfma_f32_32x32x16_f16 v[98:113], v[240:243], v[212:215], v[98:113]
	v_mfma_f32_32x32x16_f16 v[82:97], v[236:239], v[216:219], v[82:97]
	v_mfma_f32_32x32x16_f16 v[66:81], v[240:243], v[216:219], v[66:81]
	v_mfma_f32_32x32x16_f16 v[50:65], v[236:239], v[220:223], v[50:65]
	v_mfma_f32_32x32x16_f16 v[34:49], v[240:243], v[220:223], v[34:49]
	v_mfma_f32_32x32x16_f16 v[18:33], v[236:239], v[224:227], v[18:33]
	v_mfma_f32_32x32x16_f16 v[2:17], v[240:243], v[224:227], v[2:17]
	ds_read_b128 v[236:239], v193 offset:32
	ds_read_b128 v[212:215], v177 offset:32
	ds_read_b128 v[240:243], v193 offset:4640
	ds_read_b128 v[216:219], v177 offset:4640
	ds_read_b128 v[220:223], v177 offset:9248
	ds_read_b128 v[224:227], v177 offset:13856
	s_waitcnt vmcnt(4)
	ds_write_b128 v175, v[130:133]
	ds_write_b128 v175, v[134:137] offset:16
	ds_write_b128 v175, v[138:141] offset:32
	ds_write_b128 v175, v[142:145] offset:48
	global_load_dwordx4 v[130:133], v[162:163], off offset:1792
	global_load_dwordx4 v[134:137], v[162:163], off offset:1808
	global_load_dwordx4 v[138:141], v[162:163], off offset:1824
	global_load_dwordx4 v[142:145], v[162:163], off offset:1840
	s_waitcnt lgkmcnt(14)
	v_mfma_f32_32x32x16_f16 v[114:129], v[228:231], v[188:191], v[114:129]
	s_waitcnt lgkmcnt(13)
	v_mfma_f32_32x32x16_f16 v[98:113], v[232:235], v[188:191], v[98:113]
	s_waitcnt lgkmcnt(12)
	v_mfma_f32_32x32x16_f16 v[82:97], v[228:231], v[200:203], v[82:97]
	v_mfma_f32_32x32x16_f16 v[66:81], v[232:235], v[200:203], v[66:81]
	s_waitcnt lgkmcnt(11)
	v_mfma_f32_32x32x16_f16 v[50:65], v[228:231], v[204:207], v[50:65]
	v_mfma_f32_32x32x16_f16 v[34:49], v[232:235], v[204:207], v[34:49]
	s_waitcnt lgkmcnt(10)
	v_mfma_f32_32x32x16_f16 v[18:33], v[228:231], v[208:211], v[18:33]
	v_mfma_f32_32x32x16_f16 v[2:17], v[232:235], v[208:211], v[2:17]
	ds_read_b128 v[228:231], v193 offset:64
	ds_read_b128 v[188:191], v177 offset:64
	ds_read_b128 v[232:235], v193 offset:4672
	ds_read_b128 v[200:203], v177 offset:4672
	ds_read_b128 v[204:207], v177 offset:9280
	ds_read_b128 v[208:211], v177 offset:13888
	s_waitcnt vmcnt(4)
	ds_write_b128 v175, v[146:149] offset:36864
	ds_write_b128 v175, v[150:153] offset:36880
	ds_write_b128 v175, v[154:157] offset:36896
	ds_write_b128 v175, v[158:161] offset:36912
	global_load_dwordx4 v[146:149], v[178:179], off offset:1792
	global_load_dwordx4 v[150:153], v[178:179], off offset:1808
	global_load_dwordx4 v[154:157], v[178:179], off offset:1824
	global_load_dwordx4 v[158:161], v[178:179], off offset:1840
	s_waitcnt lgkmcnt(15)
	v_mfma_f32_32x32x16_f16 v[114:129], v[236:239], v[212:215], v[114:129]
	s_waitcnt lgkmcnt(15)
	v_mfma_f32_32x32x16_f16 v[98:113], v[240:243], v[212:215], v[98:113]
	s_waitcnt lgkmcnt(15)
	v_mfma_f32_32x32x16_f16 v[82:97], v[236:239], v[216:219], v[82:97]
	v_mfma_f32_32x32x16_f16 v[66:81], v[240:243], v[216:219], v[66:81]
	s_waitcnt lgkmcnt(15)
	v_mfma_f32_32x32x16_f16 v[50:65], v[236:239], v[220:223], v[50:65]
	v_mfma_f32_32x32x16_f16 v[34:49], v[240:243], v[220:223], v[34:49]
	s_waitcnt lgkmcnt(14)
	v_mfma_f32_32x32x16_f16 v[18:33], v[236:239], v[224:227], v[18:33]
	v_mfma_f32_32x32x16_f16 v[2:17], v[240:243], v[224:227], v[2:17]
	ds_read_b128 v[236:239], v193 offset:96
	ds_read_b128 v[212:215], v177 offset:96
	ds_read_b128 v[240:243], v193 offset:4704
	ds_read_b128 v[216:219], v177 offset:4704
	ds_read_b128 v[220:223], v177 offset:9312
	ds_read_b128 v[224:227], v177 offset:13920
	s_waitcnt lgkmcnt(14)
	v_mfma_f32_32x32x16_f16 v[114:129], v[228:231], v[188:191], v[114:129]
	s_waitcnt lgkmcnt(13)
	v_mfma_f32_32x32x16_f16 v[98:113], v[232:235], v[188:191], v[98:113]
	s_waitcnt lgkmcnt(12)
	v_mfma_f32_32x32x16_f16 v[82:97], v[228:231], v[200:203], v[82:97]
	v_mfma_f32_32x32x16_f16 v[66:81], v[232:235], v[200:203], v[66:81]
	s_waitcnt lgkmcnt(11)
	v_mfma_f32_32x32x16_f16 v[50:65], v[228:231], v[204:207], v[50:65]
	v_mfma_f32_32x32x16_f16 v[34:49], v[232:235], v[204:207], v[34:49]
	s_waitcnt lgkmcnt(10)
	v_mfma_f32_32x32x16_f16 v[18:33], v[228:231], v[208:211], v[18:33]
	v_mfma_f32_32x32x16_f16 v[2:17], v[232:235], v[208:211], v[2:17]
	s_waitcnt lgkmcnt(0)
	s_barrier
; DI f16v mfma32(h8v a, h8v b, f16v c) { return __builtin_amdgcn_mfma_f32_32x32x16_f16(a, b, c, 0, 0, 0); }
; template <bool GATHER>
; DI void gemm256_main(const h16* __restrict__ A, int lda, const int* __restrict__ idx, int m0,
;                      const h16* __restrict__ B, int ldb, int n0, int K, h16* lds, f16v (&acc)[4][2]) {
;     ...
;   for (int kt = 0; kt < nk; ++kt) {
;     const h16* As = lds + (kt & 1) * (512 * LDH);
;     const h16* Bs = As + 256 * LDH;
;     h16* Wn = lds + ((kt & 1) ^ 1) * (512 * LDH);
;     if (kt + 1 < nk) {
; #pragma unroll
;       for (int i = 0; i < 4; ++i) { *(u4v*)&Wn[lr * LDH + lc + 8 * i] = ra[i]; *(u4v*)&Wn[(256 + lr) * LDH + lc + 8 * i] = rb[i]; }
;     }
;     if (kt + 2 < nk) {
; #pragma unroll
;       for (int i = 0; i < 4; ++i) { ra[i] = *(const u4v*)(AP_ + 8 * i); rb[i] = *(const u4v*)(BP_ + 8 * i); }
;       ao += 64; bo += 64;
;     }
; #pragma unroll
;     for (int ks = 0; ks < 4; ++ks) {
;       h8v af[4], bf[2];
; #pragma unroll
;       for (int i = 0; i < 4; ++i) af[i] = *(const h8v*)&As[(wm * 128 + i * 32 + (lane & 31)) * LDH + ks * 16 + 8 * (lane >> 5)];
; #pragma unroll
;       for (int j = 0; j < 2; ++j) bf[j] = *(const h8v*)&Bs[(wn * 64 + j * 32 + (lane & 31)) * LDH + ks * 16 + 8 * (lane >> 5)];
; #pragma unroll
;       for (int i = 0; i < 4; ++i)
; #pragma unroll
;         for (int j = 0; j < 2; ++j) acc[i][j] = mfma32(bf[j], af[i], acc[i][j]);
;     }
;     __syncthreads();
;   }
	ds_read_b128 v[228:231], v194
	ds_read_b128 v[188:191], v192
	ds_read_b128 v[232:235], v194 offset:4608
	ds_read_b128 v[200:203], v192 offset:4608
	ds_read_b128 v[204:207], v192 offset:9216
	ds_read_b128 v[208:211], v192 offset:13824
	v_mfma_f32_32x32x16_f16 v[114:129], v[236:239], v[212:215], v[114:129]
	v_mfma_f32_32x32x16_f16 v[98:113], v[240:243], v[212:215], v[98:113]
	v_mfma_f32_32x32x16_f16 v[82:97], v[236:239], v[216:219], v[82:97]
	v_mfma_f32_32x32x16_f16 v[66:81], v[240:243], v[216:219], v[66:81]
	v_mfma_f32_32x32x16_f16 v[50:65], v[236:239], v[220:223], v[50:65]
	v_mfma_f32_32x32x16_f16 v[34:49], v[240:243], v[220:223], v[34:49]
	v_mfma_f32_32x32x16_f16 v[18:33], v[236:239], v[224:227], v[18:33]
	v_mfma_f32_32x32x16_f16 v[2:17], v[240:243], v[224:227], v[2:17]
	ds_read_b128 v[236:239], v194 offset:32
	ds_read_b128 v[212:215], v192 offset:32
	ds_read_b128 v[240:243], v194 offset:4640
	ds_read_b128 v[216:219], v192 offset:4640
	ds_read_b128 v[220:223], v192 offset:9248
	ds_read_b128 v[224:227], v192 offset:13856
	s_waitcnt vmcnt(4)
	ds_write_b128 v165, v[130:133]
	ds_write_b128 v165, v[134:137] offset:16
	ds_write_b128 v165, v[138:141] offset:32
	ds_write_b128 v165, v[142:145] offset:48
	global_load_dwordx4 v[130:133], v[162:163], off offset:1920
	global_load_dwordx4 v[134:137], v[162:163], off offset:1936
	global_load_dwordx4 v[138:141], v[162:163], off offset:1952
	global_load_dwordx4 v[142:145], v[162:163], off offset:1968
	s_waitcnt lgkmcnt(14)
	v_mfma_f32_32x32x16_f16 v[114:129], v[228:231], v[188:191], v[114:129]
	s_waitcnt lgkmcnt(13)
	v_mfma_f32_32x32x16_f16 v[98:113], v[232:235], v[188:191], v[98:113]
	s_waitcnt lgkmcnt(12)
	v_mfma_f32_32x32x16_f16 v[82:97], v[228:231], v[200:203], v[82:97]
	v_mfma_f32_32x32x16_f16 v[66:81], v[232:235], v[200:203], v[66:81]
	s_waitcnt lgkmcnt(11)
	v_mfma_f32_32x32x16_f16 v[50:65], v[228:231], v[204:207], v[50:65]
	v_mfma_f32_32x32x16_f16 v[34:49], v[232:235], v[204:207], v[34:49]
	s_waitcnt lgkmcnt(10)
	v_mfma_f32_32x32x16_f16 v[18:33], v[228:231], v[208:211], v[18:33]
	v_mfma_f32_32x32x16_f16 v[2:17], v[232:235], v[208:211], v[2:17]
	ds_read_b128 v[228:231], v194 offset:64
	ds_read_b128 v[188:191], v192 offset:64
	ds_read_b128 v[232:235], v194 offset:4672
	ds_read_b128 v[200:203], v192 offset:4672
	ds_read_b128 v[204:207], v192 offset:9280
	ds_read_b128 v[208:211], v192 offset:13888
	s_waitcnt vmcnt(4)
	ds_write_b128 v165, v[146:149] offset:36864
	ds_write_b128 v165, v[150:153] offset:36880
	ds_write_b128 v165, v[154:157] offset:36896
	ds_write_b128 v165, v[158:161] offset:36912
	global_load_dwordx4 v[146:149], v[178:179], off offset:1920
	global_load_dwordx4 v[150:153], v[178:179], off offset:1936
	global_load_dwordx4 v[154:157], v[178:179], off offset:1952
	global_load_dwordx4 v[158:161], v[178:179], off offset:1968
	s_waitcnt lgkmcnt(15)
	v_mfma_f32_32x32x16_f16 v[114:129], v[236:239], v[212:215], v[114:129]
	s_waitcnt lgkmcnt(15)
	v_mfma_f32_32x32x16_f16 v[98:113], v[240:243], v[212:215], v[98:113]
	s_waitcnt lgkmcnt(15)
	v_mfma_f32_32x32x16_f16 v[82:97], v[236:239], v[216:219], v[82:97]
	v_mfma_f32_32x32x16_f16 v[66:81], v[240:243], v[216:219], v[66:81]
	s_waitcnt lgkmcnt(15)
	v_mfma_f32_32x32x16_f16 v[50:65], v[236:239], v[220:223], v[50:65]
	v_mfma_f32_32x32x16_f16 v[34:49], v[240:243], v[220:223], v[34:49]
	s_waitcnt lgkmcnt(14)
	v_mfma_f32_32x32x16_f16 v[18:33], v[236:239], v[224:227], v[18:33]
	v_mfma_f32_32x32x16_f16 v[2:17], v[240:243], v[224:227], v[2:17]
	ds_read_b128 v[236:239], v194 offset:96
	ds_read_b128 v[212:215], v192 offset:96
	ds_read_b128 v[240:243], v194 offset:4704
	ds_read_b128 v[216:219], v192 offset:4704
	ds_read_b128 v[220:223], v192 offset:9312
	ds_read_b128 v[224:227], v192 offset:13920
	s_waitcnt lgkmcnt(14)
	v_mfma_f32_32x32x16_f16 v[114:129], v[228:231], v[188:191], v[114:129]
	s_waitcnt lgkmcnt(13)
	v_mfma_f32_32x32x16_f16 v[98:113], v[232:235], v[188:191], v[98:113]
	s_waitcnt lgkmcnt(12)
	v_mfma_f32_32x32x16_f16 v[82:97], v[228:231], v[200:203], v[82:97]
	v_mfma_f32_32x32x16_f16 v[66:81], v[232:235], v[200:203], v[66:81]
	s_waitcnt lgkmcnt(11)
	v_mfma_f32_32x32x16_f16 v[50:65], v[228:231], v[204:207], v[50:65]
	v_mfma_f32_32x32x16_f16 v[34:49], v[232:235], v[204:207], v[34:49]
	s_waitcnt lgkmcnt(10)
	v_mfma_f32_32x32x16_f16 v[18:33], v[228:231], v[208:211], v[18:33]
	v_mfma_f32_32x32x16_f16 v[2:17], v[232:235], v[208:211], v[2:17]
	s_waitcnt lgkmcnt(0)
	s_barrier
; DI f16v mfma32(h8v a, h8v b, f16v c) { return __builtin_amdgcn_mfma_f32_32x32x16_f16(a, b, c, 0, 0, 0); }
; template <bool GATHER>
; DI void gemm256_main(const h16* __restrict__ A, int lda, const int* __restrict__ idx, int m0,
;                      const h16* __restrict__ B, int ldb, int n0, int K, h16* lds, f16v (&acc)[4][2]) {
;     ...
;   for (int kt = 0; kt < nk; ++kt) {
;     const h16* As = lds + (kt & 1) * (512 * LDH);
;     const h16* Bs = As + 256 * LDH;
;     h16* Wn = lds + ((kt & 1) ^ 1) * (512 * LDH);
;     if (kt + 1 < nk) {
; #pragma unroll
;       for (int i = 0; i < 4; ++i) { *(u4v*)&Wn[lr * LDH + lc + 8 * i] = ra[i]; *(u4v*)&Wn[(256 + lr) * LDH + lc + 8 * i] = rb[i]; }
;     }
;     if (kt + 2 < nk) {
; #pragma unroll
;       for (int i = 0; i < 4; ++i) { ra[i] = *(const u4v*)(AP_ + 8 * i); rb[i] = *(const u4v*)(BP_ + 8 * i); }
;       ao += 64; bo += 64;
;     }
; #pragma unroll
;     for (int ks = 0; ks < 4; ++ks) {
;       h8v af[4], bf[2];
; #pragma unroll
;       for (int i = 0; i < 4; ++i) af[i] = *(const h8v*)&As[(wm * 128 + i * 32 + (lane & 31)) * LDH + ks * 16 + 8 * (lane >> 5)];
; #pragma unroll
;       for (int j = 0; j < 2; ++j) bf[j] = *(const h8v*)&Bs[(wn * 64 + j * 32 + (lane & 31)) * LDH + ks * 16 + 8 * (lane >> 5)];
; #pragma unroll
;       for (int i = 0; i < 4; ++i)
; #pragma unroll
;         for (int j = 0; j < 2; ++j) acc[i][j] = mfma32(bf[j], af[i], acc[i][j]);
;     }
;     __syncthreads();
;   }
	ds_read_b128 v[228:231], v193
	ds_read_b128 v[188:191], v177
	ds_read_b128 v[232:235], v193 offset:4608
	ds_read_b128 v[200:203], v177 offset:4608
	ds_read_b128 v[204:207], v177 offset:9216
	ds_read_b128 v[208:211], v177 offset:13824
	v_mfma_f32_32x32x16_f16 v[114:129], v[236:239], v[212:215], v[114:129]
	v_mfma_f32_32x32x16_f16 v[98:113], v[240:243], v[212:215], v[98:113]
	v_mfma_f32_32x32x16_f16 v[82:97], v[236:239], v[216:219], v[82:97]
	v_mfma_f32_32x32x16_f16 v[66:81], v[240:243], v[216:219], v[66:81]
	v_mfma_f32_32x32x16_f16 v[50:65], v[236:239], v[220:223], v[50:65]
	v_mfma_f32_32x32x16_f16 v[34:49], v[240:243], v[220:223], v[34:49]
	v_mfma_f32_32x32x16_f16 v[18:33], v[236:239], v[224:227], v[18:33]
	v_mfma_f32_32x32x16_f16 v[2:17], v[240:243], v[224:227], v[2:17]
	ds_read_b128 v[236:239], v193 offset:32
	ds_read_b128 v[212:215], v177 offset:32
	ds_read_b128 v[240:243], v193 offset:4640
	ds_read_b128 v[216:219], v177 offset:4640
	ds_read_b128 v[220:223], v177 offset:9248
	ds_read_b128 v[224:227], v177 offset:13856
	s_waitcnt vmcnt(4)
	ds_write_b128 v175, v[130:133]
	ds_write_b128 v175, v[134:137] offset:16
	ds_write_b128 v175, v[138:141] offset:32
	ds_write_b128 v175, v[142:145] offset:48
	s_waitcnt lgkmcnt(14)
	v_mfma_f32_32x32x16_f16 v[114:129], v[228:231], v[188:191], v[114:129]
	s_waitcnt lgkmcnt(13)
	v_mfma_f32_32x32x16_f16 v[98:113], v[232:235], v[188:191], v[98:113]
	s_waitcnt lgkmcnt(12)
	v_mfma_f32_32x32x16_f16 v[82:97], v[228:231], v[200:203], v[82:97]
	v_mfma_f32_32x32x16_f16 v[66:81], v[232:235], v[200:203], v[66:81]
	s_waitcnt lgkmcnt(11)
	v_mfma_f32_32x32x16_f16 v[50:65], v[228:231], v[204:207], v[50:65]
	v_mfma_f32_32x32x16_f16 v[34:49], v[232:235], v[204:207], v[34:49]
	s_waitcnt lgkmcnt(10)
	v_mfma_f32_32x32x16_f16 v[18:33], v[228:231], v[208:211], v[18:33]
	v_mfma_f32_32x32x16_f16 v[2:17], v[232:235], v[208:211], v[2:17]
	ds_read_b128 v[228:231], v193 offset:64
	ds_read_b128 v[188:191], v177 offset:64
	ds_read_b128 v[232:235], v193 offset:4672
	ds_read_b128 v[200:203], v177 offset:4672
	ds_read_b128 v[204:207], v177 offset:9280
	ds_read_b128 v[208:211], v177 offset:13888
	s_waitcnt vmcnt(0)
	ds_write_b128 v175, v[146:149] offset:36864
	ds_write_b128 v175, v[150:153] offset:36880
	ds_write_b128 v175, v[154:157] offset:36896
	ds_write_b128 v175, v[158:161] offset:36912
	s_waitcnt lgkmcnt(15)
	v_mfma_f32_32x32x16_f16 v[114:129], v[236:239], v[212:215], v[114:129]
	s_waitcnt lgkmcnt(15)
	v_mfma_f32_32x32x16_f16 v[98:113], v[240:243], v[212:215], v[98:113]
	s_waitcnt lgkmcnt(15)
	v_mfma_f32_32x32x16_f16 v[82:97], v[236:239], v[216:219], v[82:97]
	v_mfma_f32_32x32x16_f16 v[66:81], v[240:243], v[216:219], v[66:81]
	s_waitcnt lgkmcnt(15)
	v_mfma_f32_32x32x16_f16 v[50:65], v[236:239], v[220:223], v[50:65]
	v_mfma_f32_32x32x16_f16 v[34:49], v[240:243], v[220:223], v[34:49]
	s_waitcnt lgkmcnt(14)
	v_mfma_f32_32x32x16_f16 v[18:33], v[236:239], v[224:227], v[18:33]
	v_mfma_f32_32x32x16_f16 v[2:17], v[240:243], v[224:227], v[2:17]
	ds_read_b128 v[236:239], v193 offset:96
	ds_read_b128 v[212:215], v177 offset:96
	ds_read_b128 v[240:243], v193 offset:4704
	ds_read_b128 v[216:219], v177 offset:4704
	ds_read_b128 v[220:223], v177 offset:9312
	ds_read_b128 v[224:227], v177 offset:13920
	s_waitcnt lgkmcnt(14)
	v_mfma_f32_32x32x16_f16 v[114:129], v[228:231], v[188:191], v[114:129]
	s_waitcnt lgkmcnt(13)
	v_mfma_f32_32x32x16_f16 v[98:113], v[232:235], v[188:191], v[98:113]
	s_waitcnt lgkmcnt(12)
	v_mfma_f32_32x32x16_f16 v[82:97], v[228:231], v[200:203], v[82:97]
	v_mfma_f32_32x32x16_f16 v[66:81], v[232:235], v[200:203], v[66:81]
	s_waitcnt lgkmcnt(11)
	v_mfma_f32_32x32x16_f16 v[50:65], v[228:231], v[204:207], v[50:65]
	v_mfma_f32_32x32x16_f16 v[34:49], v[232:235], v[204:207], v[34:49]
	s_waitcnt lgkmcnt(10)
	v_mfma_f32_32x32x16_f16 v[18:33], v[228:231], v[208:211], v[18:33]
	v_mfma_f32_32x32x16_f16 v[2:17], v[232:235], v[208:211], v[2:17]
	s_waitcnt lgkmcnt(0)
	s_barrier
	ds_read_b128 v[228:231], v194
	ds_read_b128 v[188:191], v192
	ds_read_b128 v[232:235], v194 offset:4608
	ds_read_b128 v[200:203], v192 offset:4608
	ds_read_b128 v[204:207], v192 offset:9216
	ds_read_b128 v[208:211], v192 offset:13824
	v_mfma_f32_32x32x16_f16 v[114:129], v[236:239], v[212:215], v[114:129]
	v_mfma_f32_32x32x16_f16 v[98:113], v[240:243], v[212:215], v[98:113]
	v_mfma_f32_32x32x16_f16 v[82:97], v[236:239], v[216:219], v[82:97]
	v_mfma_f32_32x32x16_f16 v[66:81], v[240:243], v[216:219], v[66:81]
	v_mfma_f32_32x32x16_f16 v[50:65], v[236:239], v[220:223], v[50:65]
	v_mfma_f32_32x32x16_f16 v[34:49], v[240:243], v[220:223], v[34:49]
	v_mfma_f32_32x32x16_f16 v[18:33], v[236:239], v[224:227], v[18:33]
	v_mfma_f32_32x32x16_f16 v[2:17], v[240:243], v[224:227], v[2:17]
	ds_read_b128 v[236:239], v194 offset:32
	ds_read_b128 v[212:215], v192 offset:32
	ds_read_b128 v[240:243], v194 offset:4640
	ds_read_b128 v[216:219], v192 offset:4640
	ds_read_b128 v[220:223], v192 offset:9248
	ds_read_b128 v[224:227], v192 offset:13856
	s_waitcnt lgkmcnt(10)
	v_mfma_f32_32x32x16_f16 v[114:129], v[228:231], v[188:191], v[114:129]
	s_waitcnt lgkmcnt(9)
	v_mfma_f32_32x32x16_f16 v[98:113], v[232:235], v[188:191], v[98:113]
	s_waitcnt lgkmcnt(8)
	v_mfma_f32_32x32x16_f16 v[82:97], v[228:231], v[200:203], v[82:97]
	v_mfma_f32_32x32x16_f16 v[66:81], v[232:235], v[200:203], v[66:81]
	s_waitcnt lgkmcnt(7)
	v_mfma_f32_32x32x16_f16 v[50:65], v[228:231], v[204:207], v[50:65]
	v_mfma_f32_32x32x16_f16 v[34:49], v[232:235], v[204:207], v[34:49]
	s_waitcnt lgkmcnt(6)
; DI f16v mfma32(h8v a, h8v b, f16v c) { return __builtin_amdgcn_mfma_f32_32x32x16_f16(a, b, c, 0, 0, 0); }
; template <bool GATHER>
; DI void gemm256_main(const h16* __restrict__ A, int lda, const int* __restrict__ idx, int m0,
;                      const h16* __restrict__ B, int ldb, int n0, int K, h16* lds, f16v (&acc)[4][2]) {
;     ...
;     for (int ks = 0; ks < 4; ++ks) {
;       h8v af[4], bf[2];
; #pragma unroll
;       for (int i = 0; i < 4; ++i) af[i] = *(const h8v*)&As[(wm * 128 + i * 32 + (lane & 31)) * LDH + ks * 16 + 8 * (lane >> 5)];
; #pragma unroll
;       for (int j = 0; j < 2; ++j) bf[j] = *(const h8v*)&Bs[(wn * 64 + j * 32 + (lane & 31)) * LDH + ks * 16 + 8 * (lane >> 5)];
; #pragma unroll
;       for (int i = 0; i < 4; ++i)
; #pragma unroll
;         for (int j = 0; j < 2; ++j) acc[i][j] = mfma32(bf[j], af[i], acc[i][j]);
;     }
;     __syncthreads();
;   }
; DI void phase_resid_gemm(const Params& p, const h16* A, int lda, const h16* W, int K, const float* xres, int bid, int nb, h16* lds) {
;     ...
;     gemm256_epilogue(acc, m0, n0, [&](int m, int n, f4v v0, f4v v1) {
;       const f4v x0 = *(const f4v*)&xres[(size_t)m * DM + n], x1 = *(const f4v*)&xres[(size_t)m * DM + n + 32];
;       *(f4v*)&out[(size_t)m * DM + n] = ALPHA * x0 + v0;
;       *(f4v*)&out[(size_t)m * DM + n + 32] = ALPHA * x1 + v1;
;     });
	v_mfma_f32_32x32x16_f16 v[18:33], v[228:231], v[208:211], v[18:33]
	v_mfma_f32_32x32x16_f16 v[2:17], v[232:235], v[208:211], v[2:17]
	ds_read_b128 v[228:231], v194 offset:64
	ds_read_b128 v[188:191], v192 offset:64
	ds_read_b128 v[232:235], v194 offset:4672
	ds_read_b128 v[200:203], v192 offset:4672
	ds_read_b128 v[204:207], v192 offset:9280
	ds_read_b128 v[208:211], v192 offset:13888
	s_waitcnt lgkmcnt(10)
	v_mfma_f32_32x32x16_f16 v[114:129], v[236:239], v[212:215], v[114:129]
	s_waitcnt lgkmcnt(9)
	v_mfma_f32_32x32x16_f16 v[98:113], v[240:243], v[212:215], v[98:113]
	s_waitcnt lgkmcnt(8)
	v_mfma_f32_32x32x16_f16 v[82:97], v[236:239], v[216:219], v[82:97]
	v_mfma_f32_32x32x16_f16 v[66:81], v[240:243], v[216:219], v[66:81]
	s_waitcnt lgkmcnt(7)
	v_mfma_f32_32x32x16_f16 v[50:65], v[236:239], v[220:223], v[50:65]
	v_mfma_f32_32x32x16_f16 v[34:49], v[240:243], v[220:223], v[34:49]
	s_waitcnt lgkmcnt(6)
	v_mfma_f32_32x32x16_f16 v[18:33], v[236:239], v[224:227], v[18:33]
	v_mfma_f32_32x32x16_f16 v[2:17], v[240:243], v[224:227], v[2:17]
	ds_read_b128 v[236:239], v194 offset:96
	ds_read_b128 v[212:215], v192 offset:96
	ds_read_b128 v[240:243], v194 offset:4704
	ds_read_b128 v[216:219], v192 offset:4704
	ds_read_b128 v[220:223], v192 offset:9312
	ds_read_b128 v[224:227], v192 offset:13920
	s_waitcnt lgkmcnt(10)
	v_mfma_f32_32x32x16_f16 v[114:129], v[228:231], v[188:191], v[114:129]
	s_waitcnt lgkmcnt(9)
	v_mfma_f32_32x32x16_f16 v[98:113], v[232:235], v[188:191], v[98:113]
	s_waitcnt lgkmcnt(8)
	v_mfma_f32_32x32x16_f16 v[82:97], v[228:231], v[200:203], v[82:97]
	v_mfma_f32_32x32x16_f16 v[66:81], v[232:235], v[200:203], v[66:81]
	s_waitcnt lgkmcnt(7)
	v_mfma_f32_32x32x16_f16 v[50:65], v[228:231], v[204:207], v[50:65]
	v_mfma_f32_32x32x16_f16 v[34:49], v[232:235], v[204:207], v[34:49]
	s_waitcnt lgkmcnt(6)
	v_mfma_f32_32x32x16_f16 v[18:33], v[228:231], v[208:211], v[18:33]
	v_mfma_f32_32x32x16_f16 v[2:17], v[232:235], v[208:211], v[2:17]
	s_waitcnt lgkmcnt(0)
	v_mfma_f32_32x32x16_f16 v[114:129], v[236:239], v[212:215], v[114:129]
	v_mfma_f32_32x32x16_f16 v[98:113], v[240:243], v[212:215], v[98:113]
	v_mfma_f32_32x32x16_f16 v[82:97], v[236:239], v[216:219], v[82:97]
	v_mfma_f32_32x32x16_f16 v[66:81], v[240:243], v[216:219], v[66:81]
	v_mfma_f32_32x32x16_f16 v[50:65], v[236:239], v[220:223], v[50:65]
	v_mfma_f32_32x32x16_f16 v[34:49], v[240:243], v[220:223], v[34:49]
	v_mfma_f32_32x32x16_f16 v[18:33], v[236:239], v[224:227], v[18:33]
	v_mfma_f32_32x32x16_f16 v[2:17], v[240:243], v[224:227], v[2:17]
	s_nop 15
	v_mov_b32_e32 v188, 0x358637bd
	v_mov_b32_e32 v189, 0x3727c5ac
	v_mov_b32_e32 v190, 0x2100
	v_mov_b32_e32 v191, 0x1400
	v_mov_b32_e32 v192, 0x7f800000
	v_mov_b32_e32 v193, 0x7fc00000
	v_mov_b32_e32 v194, 0xff800000
	v_mov_b32_e32 v199, 0xf149f2ca
	v_mov_b32_e32 v204, 0x7fffec00
	v_mov_b32_e32 v205, 0xff7fc99e
	v_mov_b32_e32 v206, 0x840000
	v_mov_b32_e32 v207, 0xb00000
	v_mov_b32_e32 v208, 0xdc0000
	v_mov_b32_e32 v209, 0x1080000
	v_mov_b32_e32 v210, 0x1340000
	v_mov_b32_e32 v211, 0x420000
	v_mov_b32_e32 v212, 0x580000
	v_mov_b32_e32 v213, 0x6e0000
	v_mov_b32_e32 v214, 0x9a0000
	v_mov_b32_e32 v1, v180
	s_nop 15
	s_cselect_b32 s60, 1, 0
	s_barrier
	v_readfirstlane_b32 s66, v180
	s_mov_b32 s69, s5
	s_mov_b32 s65, s6
	s_lshr_b32 s66, s66, 6
	s_and_b32 s67, s66, 3
	s_lshr_b32 s68, s66, 2
	s_lshl_b32 s70, s67, 6
	s_add_i32 s70, s70, s69
	s_lshl_b32 s71, s68, 7
	s_add_i32 s71, s71, s65
	s_mul_i32 s72, s66, 0x4400
	s_add_i32 s72, s72, 16
	v_and_b32_e32 v136, 63, v180
	v_and_b32_e32 v137, 31, v136
	v_lshrrev_b32_e32 v138, 5, v136
	v_mul_u32_u24_e32 v130, 0x110, v137
	v_lshl_add_u32 v130, v138, 4, v130
	v_add_u32_e32 v130, s72, v130
	v_lshrrev_b32_e32 v137, 4, v136
	v_and_b32_e32 v138, 15, v136
	v_mul_u32_u24_e32 v131, 0x110, v137
	v_lshl_add_u32 v131, v138, 4, v131
	v_add_u32_e32 v131, s72, v131
	v_add_u32_e32 v137, s71, v137
	v_lshl_add_u32 v138, v138, 2, s70
	v_lshlrev_b32_e32 v138, 2, v138
	v_mov_b32_e32 v139, v0
	s_mov_b32 s73, 0x1000
	v_mov_b64_e32 v[132:133], s[2:3]
	v_mad_u64_u32 v[132:133], s[74:75], v137, s73, v[132:133]
	v_lshl_add_u64 v[132:133], v[132:133], 0, v[138:139]
	v_mov_b64_e32 v[134:135], s[18:19]
	v_mad_u64_u32 v[134:135], s[74:75], v137, s73, v[134:135]
	v_lshl_add_u64 v[134:135], v[134:135], 0, v[138:139]
	s_mov_b32 s76, 0x4000
	s_mov_b32 s77, 0
	ds_write_b128 v130, v[114:117]
	ds_write_b128 v130, v[118:121] offset:32
	ds_write_b128 v130, v[122:125] offset:64
	ds_write_b128 v130, v[126:129] offset:96
	ds_write_b128 v130, v[98:101] offset:128
	ds_write_b128 v130, v[102:105] offset:160
	ds_write_b128 v130, v[106:109] offset:192
	ds_write_b128 v130, v[110:113] offset:224
	ds_write_b128 v130, v[82:85] offset:8704
	ds_write_b128 v130, v[86:89] offset:8736
	ds_write_b128 v130, v[90:93] offset:8768
	ds_write_b128 v130, v[94:97] offset:8800
	ds_write_b128 v130, v[66:69] offset:8832
	ds_write_b128 v130, v[70:73] offset:8864
	ds_write_b128 v130, v[74:77] offset:8896
	ds_write_b128 v130, v[78:81] offset:8928
	global_load_dwordx4 v[224:227], v[132:133], off
	v_lshl_add_u64 v[132:133], v[132:133], 0, s[76:77]
	global_load_dwordx4 v[228:231], v[132:133], off
	v_lshl_add_u64 v[132:133], v[132:133], 0, s[76:77]
	global_load_dwordx4 v[232:235], v[132:133], off
	v_lshl_add_u64 v[132:133], v[132:133], 0, s[76:77]
	global_load_dwordx4 v[236:239], v[132:133], off
	v_lshl_add_u64 v[132:133], v[132:133], 0, s[76:77]
	global_load_dwordx4 v[240:243], v[132:133], off
	v_lshl_add_u64 v[132:133], v[132:133], 0, s[76:77]
	global_load_dwordx4 v[244:247], v[132:133], off
	v_lshl_add_u64 v[132:133], v[132:133], 0, s[76:77]
	global_load_dwordx4 v[176:179], v[132:133], off
	v_lshl_add_u64 v[132:133], v[132:133], 0, s[76:77]
	global_load_dwordx4 v[200:203], v[132:133], off
	v_lshl_add_u64 v[132:133], v[132:133], 0, s[76:77]
	ds_read_b128 v[140:143], v131
	ds_read_b128 v[144:147], v131 offset:1088
	ds_read_b128 v[148:151], v131 offset:2176
	ds_read_b128 v[152:155], v131 offset:3264
	ds_read_b128 v[156:159], v131 offset:4352
	ds_read_b128 v[160:163], v131 offset:5440
	ds_read_b128 v[216:219], v131 offset:6528
	ds_read_b128 v[220:223], v131 offset:7616
	s_waitcnt vmcnt(7) lgkmcnt(7)
; DI void phase_resid_gemm(const Params& p, const h16* A, int lda, const h16* W, int K, const float* xres, int bid, int nb, h16* lds) {
;     ...
;     gemm256_epilogue(acc, m0, n0, [&](int m, int n, f4v v0, f4v v1) {
;       const f4v x0 = *(const f4v*)&xres[(size_t)m * DM + n], x1 = *(const f4v*)&xres[(size_t)m * DM + n + 32];
;       *(f4v*)&out[(size_t)m * DM + n] = ALPHA * x0 + v0;
;       *(f4v*)&out[(size_t)m * DM + n + 32] = ALPHA * x1 + v1;
;     });
	v_pk_fma_f32 v[140:141], v[224:225], s[10:11], v[140:141] op_sel_hi:[1,0,1]
	v_pk_fma_f32 v[142:143], v[226:227], s[10:11], v[142:143] op_sel_hi:[1,0,1]
	global_store_dwordx4 v[134:135], v[140:143], off
	v_lshl_add_u64 v[134:135], v[134:135], 0, s[76:77]
	s_waitcnt vmcnt(7) lgkmcnt(6)
	v_pk_fma_f32 v[144:145], v[228:229], s[10:11], v[144:145] op_sel_hi:[1,0,1]
	v_pk_fma_f32 v[146:147], v[230:231], s[10:11], v[146:147] op_sel_hi:[1,0,1]
	global_store_dwordx4 v[134:135], v[144:147], off
	v_lshl_add_u64 v[134:135], v[134:135], 0, s[76:77]
	s_waitcnt vmcnt(7) lgkmcnt(5)
	v_pk_fma_f32 v[148:149], v[232:233], s[10:11], v[148:149] op_sel_hi:[1,0,1]
	v_pk_fma_f32 v[150:151], v[234:235], s[10:11], v[150:151] op_sel_hi:[1,0,1]
	global_store_dwordx4 v[134:135], v[148:151], off
	v_lshl_add_u64 v[134:135], v[134:135], 0, s[76:77]
	s_waitcnt vmcnt(7) lgkmcnt(4)
	v_pk_fma_f32 v[152:153], v[236:237], s[10:11], v[152:153] op_sel_hi:[1,0,1]
	v_pk_fma_f32 v[154:155], v[238:239], s[10:11], v[154:155] op_sel_hi:[1,0,1]
	global_store_dwordx4 v[134:135], v[152:155], off
	v_lshl_add_u64 v[134:135], v[134:135], 0, s[76:77]
	s_waitcnt vmcnt(7) lgkmcnt(3)
	v_pk_fma_f32 v[156:157], v[240:241], s[10:11], v[156:157] op_sel_hi:[1,0,1]
	v_pk_fma_f32 v[158:159], v[242:243], s[10:11], v[158:159] op_sel_hi:[1,0,1]
	global_store_dwordx4 v[134:135], v[156:159], off
	v_lshl_add_u64 v[134:135], v[134:135], 0, s[76:77]
	s_waitcnt vmcnt(7) lgkmcnt(2)
	v_pk_fma_f32 v[160:161], v[244:245], s[10:11], v[160:161] op_sel_hi:[1,0,1]
	v_pk_fma_f32 v[162:163], v[246:247], s[10:11], v[162:163] op_sel_hi:[1,0,1]
	global_store_dwordx4 v[134:135], v[160:163], off
	v_lshl_add_u64 v[134:135], v[134:135], 0, s[76:77]
	s_waitcnt vmcnt(7) lgkmcnt(1)
	v_pk_fma_f32 v[216:217], v[176:177], s[10:11], v[216:217] op_sel_hi:[1,0,1]
	v_pk_fma_f32 v[218:219], v[178:179], s[10:11], v[218:219] op_sel_hi:[1,0,1]
	global_store_dwordx4 v[134:135], v[216:219], off
	v_lshl_add_u64 v[134:135], v[134:135], 0, s[76:77]
	s_waitcnt vmcnt(7) lgkmcnt(0)
	v_pk_fma_f32 v[220:221], v[200:201], s[10:11], v[220:221] op_sel_hi:[1,0,1]
	v_pk_fma_f32 v[222:223], v[202:203], s[10:11], v[222:223] op_sel_hi:[1,0,1]
	global_store_dwordx4 v[134:135], v[220:223], off
	v_lshl_add_u64 v[134:135], v[134:135], 0, s[76:77]
	s_nop 1
	global_load_dwordx4 v[224:227], v[132:133], off
	v_lshl_add_u64 v[132:133], v[132:133], 0, s[76:77]
	global_load_dwordx4 v[228:231], v[132:133], off
	v_lshl_add_u64 v[132:133], v[132:133], 0, s[76:77]
	global_load_dwordx4 v[232:235], v[132:133], off
	v_lshl_add_u64 v[132:133], v[132:133], 0, s[76:77]
	global_load_dwordx4 v[236:239], v[132:133], off
	v_lshl_add_u64 v[132:133], v[132:133], 0, s[76:77]
	global_load_dwordx4 v[240:243], v[132:133], off
	v_lshl_add_u64 v[132:133], v[132:133], 0, s[76:77]
	global_load_dwordx4 v[244:247], v[132:133], off
	v_lshl_add_u64 v[132:133], v[132:133], 0, s[76:77]
	global_load_dwordx4 v[176:179], v[132:133], off
	v_lshl_add_u64 v[132:133], v[132:133], 0, s[76:77]
	global_load_dwordx4 v[200:203], v[132:133], off
	v_lshl_add_u64 v[132:133], v[132:133], 0, s[76:77]
	ds_read_b128 v[140:143], v131 offset:8704
	ds_read_b128 v[144:147], v131 offset:9792
	ds_read_b128 v[148:151], v131 offset:10880
	ds_read_b128 v[152:155], v131 offset:11968
	ds_read_b128 v[156:159], v131 offset:13056
	ds_read_b128 v[160:163], v131 offset:14144
	ds_read_b128 v[216:219], v131 offset:15232
	ds_read_b128 v[220:223], v131 offset:16320
	s_waitcnt vmcnt(7) lgkmcnt(7)
	v_pk_fma_f32 v[140:141], v[224:225], s[10:11], v[140:141] op_sel_hi:[1,0,1]
	v_pk_fma_f32 v[142:143], v[226:227], s[10:11], v[142:143] op_sel_hi:[1,0,1]
	global_store_dwordx4 v[134:135], v[140:143], off
	v_lshl_add_u64 v[134:135], v[134:135], 0, s[76:77]
	s_waitcnt vmcnt(7) lgkmcnt(6)
	v_pk_fma_f32 v[144:145], v[228:229], s[10:11], v[144:145] op_sel_hi:[1,0,1]
	v_pk_fma_f32 v[146:147], v[230:231], s[10:11], v[146:147] op_sel_hi:[1,0,1]
	global_store_dwordx4 v[134:135], v[144:147], off
	v_lshl_add_u64 v[134:135], v[134:135], 0, s[76:77]
	s_waitcnt vmcnt(7) lgkmcnt(5)
	v_pk_fma_f32 v[148:149], v[232:233], s[10:11], v[148:149] op_sel_hi:[1,0,1]
	v_pk_fma_f32 v[150:151], v[234:235], s[10:11], v[150:151] op_sel_hi:[1,0,1]
	global_store_dwordx4 v[134:135], v[148:151], off
	v_lshl_add_u64 v[134:135], v[134:135], 0, s[76:77]
	s_waitcnt vmcnt(7) lgkmcnt(4)
	v_pk_fma_f32 v[152:153], v[236:237], s[10:11], v[152:153] op_sel_hi:[1,0,1]
	v_pk_fma_f32 v[154:155], v[238:239], s[10:11], v[154:155] op_sel_hi:[1,0,1]
	global_store_dwordx4 v[134:135], v[152:155], off
	v_lshl_add_u64 v[134:135], v[134:135], 0, s[76:77]
	s_waitcnt vmcnt(7) lgkmcnt(3)
	v_pk_fma_f32 v[156:157], v[240:241], s[10:11], v[156:157] op_sel_hi:[1,0,1]
	v_pk_fma_f32 v[158:159], v[242:243], s[10:11], v[158:159] op_sel_hi:[1,0,1]
	global_store_dwordx4 v[134:135], v[156:159], off
	v_lshl_add_u64 v[134:135], v[134:135], 0, s[76:77]
	s_waitcnt vmcnt(7) lgkmcnt(2)
	v_pk_fma_f32 v[160:161], v[244:245], s[10:11], v[160:161] op_sel_hi:[1,0,1]
	v_pk_fma_f32 v[162:163], v[246:247], s[10:11], v[162:163] op_sel_hi:[1,0,1]
	global_store_dwordx4 v[134:135], v[160:163], off
	v_lshl_add_u64 v[134:135], v[134:135], 0, s[76:77]
	s_waitcnt vmcnt(7) lgkmcnt(1)
	v_pk_fma_f32 v[216:217], v[176:177], s[10:11], v[216:217] op_sel_hi:[1,0,1]
	v_pk_fma_f32 v[218:219], v[178:179], s[10:11], v[218:219] op_sel_hi:[1,0,1]
	global_store_dwordx4 v[134:135], v[216:219], off
	v_lshl_add_u64 v[134:135], v[134:135], 0, s[76:77]
	s_waitcnt vmcnt(7) lgkmcnt(0)
; DI void phase_resid_gemm(const Params& p, const h16* A, int lda, const h16* W, int K, const float* xres, int bid, int nb, h16* lds) {
;     ...
;     gemm256_epilogue(acc, m0, n0, [&](int m, int n, f4v v0, f4v v1) {
;       const f4v x0 = *(const f4v*)&xres[(size_t)m * DM + n], x1 = *(const f4v*)&xres[(size_t)m * DM + n + 32];
;       *(f4v*)&out[(size_t)m * DM + n] = ALPHA * x0 + v0;
;       *(f4v*)&out[(size_t)m * DM + n + 32] = ALPHA * x1 + v1;
;     });
	v_pk_fma_f32 v[220:221], v[200:201], s[10:11], v[220:221] op_sel_hi:[1,0,1]
	v_pk_fma_f32 v[222:223], v[202:203], s[10:11], v[222:223] op_sel_hi:[1,0,1]
	global_store_dwordx4 v[134:135], v[220:223], off
	v_lshl_add_u64 v[134:135], v[134:135], 0, s[76:77]
	s_nop 1
	ds_write_b128 v130, v[50:53]
	ds_write_b128 v130, v[54:57] offset:32
	ds_write_b128 v130, v[58:61] offset:64
	ds_write_b128 v130, v[62:65] offset:96
	ds_write_b128 v130, v[34:37] offset:128
	ds_write_b128 v130, v[38:41] offset:160
	ds_write_b128 v130, v[42:45] offset:192
	ds_write_b128 v130, v[46:49] offset:224
	ds_write_b128 v130, v[18:21] offset:8704
	ds_write_b128 v130, v[22:25] offset:8736
	ds_write_b128 v130, v[26:29] offset:8768
	ds_write_b128 v130, v[30:33] offset:8800
	ds_write_b128 v130, v[2:5] offset:8832
	ds_write_b128 v130, v[6:9] offset:8864
	ds_write_b128 v130, v[10:13] offset:8896
	ds_write_b128 v130, v[14:17] offset:8928
	global_load_dwordx4 v[224:227], v[132:133], off
	v_lshl_add_u64 v[132:133], v[132:133], 0, s[76:77]
	global_load_dwordx4 v[228:231], v[132:133], off
	v_lshl_add_u64 v[132:133], v[132:133], 0, s[76:77]
	global_load_dwordx4 v[232:235], v[132:133], off
	v_lshl_add_u64 v[132:133], v[132:133], 0, s[76:77]
	global_load_dwordx4 v[236:239], v[132:133], off
	v_lshl_add_u64 v[132:133], v[132:133], 0, s[76:77]
	global_load_dwordx4 v[240:243], v[132:133], off
	v_lshl_add_u64 v[132:133], v[132:133], 0, s[76:77]
	global_load_dwordx4 v[244:247], v[132:133], off
	v_lshl_add_u64 v[132:133], v[132:133], 0, s[76:77]
	global_load_dwordx4 v[176:179], v[132:133], off
	v_lshl_add_u64 v[132:133], v[132:133], 0, s[76:77]
	global_load_dwordx4 v[200:203], v[132:133], off
	v_lshl_add_u64 v[132:133], v[132:133], 0, s[76:77]
	ds_read_b128 v[140:143], v131
	ds_read_b128 v[144:147], v131 offset:1088
	ds_read_b128 v[148:151], v131 offset:2176
	ds_read_b128 v[152:155], v131 offset:3264
	ds_read_b128 v[156:159], v131 offset:4352
	ds_read_b128 v[160:163], v131 offset:5440
	ds_read_b128 v[216:219], v131 offset:6528
	ds_read_b128 v[220:223], v131 offset:7616
	s_waitcnt vmcnt(7) lgkmcnt(7)
	v_pk_fma_f32 v[140:141], v[224:225], s[10:11], v[140:141] op_sel_hi:[1,0,1]
	v_pk_fma_f32 v[142:143], v[226:227], s[10:11], v[142:143] op_sel_hi:[1,0,1]
	global_store_dwordx4 v[134:135], v[140:143], off
	v_lshl_add_u64 v[134:135], v[134:135], 0, s[76:77]
	s_waitcnt vmcnt(7) lgkmcnt(6)
	v_pk_fma_f32 v[144:145], v[228:229], s[10:11], v[144:145] op_sel_hi:[1,0,1]
	v_pk_fma_f32 v[146:147], v[230:231], s[10:11], v[146:147] op_sel_hi:[1,0,1]
	global_store_dwordx4 v[134:135], v[144:147], off
	v_lshl_add_u64 v[134:135], v[134:135], 0, s[76:77]
	s_waitcnt vmcnt(7) lgkmcnt(5)
	v_pk_fma_f32 v[148:149], v[232:233], s[10:11], v[148:149] op_sel_hi:[1,0,1]
	v_pk_fma_f32 v[150:151], v[234:235], s[10:11], v[150:151] op_sel_hi:[1,0,1]
	global_store_dwordx4 v[134:135], v[148:151], off
	v_lshl_add_u64 v[134:135], v[134:135], 0, s[76:77]
	s_waitcnt vmcnt(7) lgkmcnt(4)
	v_pk_fma_f32 v[152:153], v[236:237], s[10:11], v[152:153] op_sel_hi:[1,0,1]
	v_pk_fma_f32 v[154:155], v[238:239], s[10:11], v[154:155] op_sel_hi:[1,0,1]
	global_store_dwordx4 v[134:135], v[152:155], off
	v_lshl_add_u64 v[134:135], v[134:135], 0, s[76:77]
	s_waitcnt vmcnt(7) lgkmcnt(3)
	v_pk_fma_f32 v[156:157], v[240:241], s[10:11], v[156:157] op_sel_hi:[1,0,1]
	v_pk_fma_f32 v[158:159], v[242:243], s[10:11], v[158:159] op_sel_hi:[1,0,1]
	global_store_dwordx4 v[134:135], v[156:159], off
	v_lshl_add_u64 v[134:135], v[134:135], 0, s[76:77]
	s_waitcnt vmcnt(7) lgkmcnt(2)
	v_pk_fma_f32 v[160:161], v[244:245], s[10:11], v[160:161] op_sel_hi:[1,0,1]
	v_pk_fma_f32 v[162:163], v[246:247], s[10:11], v[162:163] op_sel_hi:[1,0,1]
	global_store_dwordx4 v[134:135], v[160:163], off
	v_lshl_add_u64 v[134:135], v[134:135], 0, s[76:77]
	s_waitcnt vmcnt(7) lgkmcnt(1)
; DI void phase_resid_gemm(const Params& p, const h16* A, int lda, const h16* W, int K, const float* xres, int bid, int nb, h16* lds) {
;     ...
;   for (int u = bid; u < 64 * 4; u += nb) {
;     const int m0 = (u >> 2) * 256, n0 = (u & 3) * 256;
;     f16v acc[4][2]; acc256_zero(acc);
;     gemm256_main<false>(A, lda, nullptr, m0, W, K, n0, K, lds, acc);
;     gemm256_epilogue(acc, m0, n0, [&](int m, int n, f4v v0, f4v v1) {
;       const f4v x0 = *(const f4v*)&xres[(size_t)m * DM + n], x1 = *(const f4v*)&xres[(size_t)m * DM + n + 32];
;       *(f4v*)&out[(size_t)m * DM + n] = ALPHA * x0 + v0;
;       *(f4v*)&out[(size_t)m * DM + n + 32] = ALPHA * x1 + v1;
;     });
	v_pk_fma_f32 v[216:217], v[176:177], s[10:11], v[216:217] op_sel_hi:[1,0,1]
	v_pk_fma_f32 v[218:219], v[178:179], s[10:11], v[218:219] op_sel_hi:[1,0,1]
	global_store_dwordx4 v[134:135], v[216:219], off
	v_lshl_add_u64 v[134:135], v[134:135], 0, s[76:77]
	s_waitcnt vmcnt(7) lgkmcnt(0)
	v_pk_fma_f32 v[220:221], v[200:201], s[10:11], v[220:221] op_sel_hi:[1,0,1]
	v_pk_fma_f32 v[222:223], v[202:203], s[10:11], v[222:223] op_sel_hi:[1,0,1]
	global_store_dwordx4 v[134:135], v[220:223], off
	v_lshl_add_u64 v[134:135], v[134:135], 0, s[76:77]
	s_nop 1
	global_load_dwordx4 v[224:227], v[132:133], off
	v_lshl_add_u64 v[132:133], v[132:133], 0, s[76:77]
	global_load_dwordx4 v[228:231], v[132:133], off
	v_lshl_add_u64 v[132:133], v[132:133], 0, s[76:77]
	global_load_dwordx4 v[232:235], v[132:133], off
	v_lshl_add_u64 v[132:133], v[132:133], 0, s[76:77]
	global_load_dwordx4 v[236:239], v[132:133], off
	v_lshl_add_u64 v[132:133], v[132:133], 0, s[76:77]
	global_load_dwordx4 v[240:243], v[132:133], off
	v_lshl_add_u64 v[132:133], v[132:133], 0, s[76:77]
	global_load_dwordx4 v[244:247], v[132:133], off
	v_lshl_add_u64 v[132:133], v[132:133], 0, s[76:77]
	global_load_dwordx4 v[176:179], v[132:133], off
	v_lshl_add_u64 v[132:133], v[132:133], 0, s[76:77]
	global_load_dwordx4 v[200:203], v[132:133], off
	v_lshl_add_u64 v[132:133], v[132:133], 0, s[76:77]
	ds_read_b128 v[140:143], v131 offset:8704
	ds_read_b128 v[144:147], v131 offset:9792
	ds_read_b128 v[148:151], v131 offset:10880
	ds_read_b128 v[152:155], v131 offset:11968
	ds_read_b128 v[156:159], v131 offset:13056
	ds_read_b128 v[160:163], v131 offset:14144
	ds_read_b128 v[216:219], v131 offset:15232
	ds_read_b128 v[220:223], v131 offset:16320
	s_waitcnt vmcnt(7) lgkmcnt(7)
	v_pk_fma_f32 v[140:141], v[224:225], s[10:11], v[140:141] op_sel_hi:[1,0,1]
	v_pk_fma_f32 v[142:143], v[226:227], s[10:11], v[142:143] op_sel_hi:[1,0,1]
	global_store_dwordx4 v[134:135], v[140:143], off
	v_lshl_add_u64 v[134:135], v[134:135], 0, s[76:77]
	s_waitcnt vmcnt(7) lgkmcnt(6)
	v_pk_fma_f32 v[144:145], v[228:229], s[10:11], v[144:145] op_sel_hi:[1,0,1]
	v_pk_fma_f32 v[146:147], v[230:231], s[10:11], v[146:147] op_sel_hi:[1,0,1]
	global_store_dwordx4 v[134:135], v[144:147], off
	v_lshl_add_u64 v[134:135], v[134:135], 0, s[76:77]
	s_waitcnt vmcnt(7) lgkmcnt(5)
	v_pk_fma_f32 v[148:149], v[232:233], s[10:11], v[148:149] op_sel_hi:[1,0,1]
	v_pk_fma_f32 v[150:151], v[234:235], s[10:11], v[150:151] op_sel_hi:[1,0,1]
	global_store_dwordx4 v[134:135], v[148:151], off
	v_lshl_add_u64 v[134:135], v[134:135], 0, s[76:77]
	s_waitcnt vmcnt(7) lgkmcnt(4)
	v_pk_fma_f32 v[152:153], v[236:237], s[10:11], v[152:153] op_sel_hi:[1,0,1]
	v_pk_fma_f32 v[154:155], v[238:239], s[10:11], v[154:155] op_sel_hi:[1,0,1]
	global_store_dwordx4 v[134:135], v[152:155], off
	v_lshl_add_u64 v[134:135], v[134:135], 0, s[76:77]
	s_waitcnt vmcnt(7) lgkmcnt(3)
	v_pk_fma_f32 v[156:157], v[240:241], s[10:11], v[156:157] op_sel_hi:[1,0,1]
	v_pk_fma_f32 v[158:159], v[242:243], s[10:11], v[158:159] op_sel_hi:[1,0,1]
	global_store_dwordx4 v[134:135], v[156:159], off
	v_lshl_add_u64 v[134:135], v[134:135], 0, s[76:77]
	s_waitcnt vmcnt(7) lgkmcnt(2)
	v_pk_fma_f32 v[160:161], v[244:245], s[10:11], v[160:161] op_sel_hi:[1,0,1]
	v_pk_fma_f32 v[162:163], v[246:247], s[10:11], v[162:163] op_sel_hi:[1,0,1]
	global_store_dwordx4 v[134:135], v[160:163], off
	v_lshl_add_u64 v[134:135], v[134:135], 0, s[76:77]
	s_waitcnt vmcnt(7) lgkmcnt(1)
	v_pk_fma_f32 v[216:217], v[176:177], s[10:11], v[216:217] op_sel_hi:[1,0,1]
	v_pk_fma_f32 v[218:219], v[178:179], s[10:11], v[218:219] op_sel_hi:[1,0,1]
	global_store_dwordx4 v[134:135], v[216:219], off
	v_lshl_add_u64 v[134:135], v[134:135], 0, s[76:77]
	s_waitcnt vmcnt(7) lgkmcnt(0)
	v_pk_fma_f32 v[220:221], v[200:201], s[10:11], v[220:221] op_sel_hi:[1,0,1]
	v_pk_fma_f32 v[222:223], v[202:203], s[10:11], v[222:223] op_sel_hi:[1,0,1]
	global_store_dwordx4 v[134:135], v[220:223], off
	v_lshl_add_u64 v[134:135], v[134:135], 0, s[76:77]
	s_nop 1
	s_cmp_eq_u32 s60, 1
	s_cbranch_scc0 .LBB0_1354
